# in-proj GEMMs (phases 1 and 7): B rows restaged so the two LDS halves hold adjacent 64B column segments; epilogue exchanges half-rows by DPP and stores full 128B lines
# speedup vs baseline: 1.0467x; 1.0178x over previous
; DI int opaque_tid() { int t = threadIdx.x; asm volatile("" : "+v"(t)); return t; }
; #define PG8_STAGE(bufoff, gbase, voff) do { _Pragma("unroll") for (int _i = 0; _i < 2; ++_i) \
;         __builtin_amdgcn_global_load_lds((const unsigned*)((const char*)(gbase) + (voff)[_i]), (LAS unsigned*)(lds + (bufoff) + ldsw + _i * 8192), 16, 0, 0); } while (0)
; #define PG8_WAIT_V(n) asm volatile("s_waitcnt vmcnt(" #n ")" ::: "memory")
; #define PG8_BAR __builtin_amdgcn_s_barrier()
; template <class Epi, class Sched>
; DI void gemm_phase(LAS unsigned char* lds, const Gemm g, const Sched& S, const Epi& E) {
;     const int tid = opaque_tid(), wid = __builtin_amdgcn_readfirstlane(tid >> 6), lane = tid & 63, wr = wid >> 2, wc = wid & 3, fr = lane & 15, fq = lane >> 4;
;     const int K = g.ld, nt = g.K / BK;
;     unsigned voffA[2], voffB[2];
; #pragma unroll
;     for (int i = 0; i < 2; ++i) { int R, C; stage_rc(tid * 16 + i * 8192, R, C); const int Rb = Epi::PERM ? ((R & ~31) + perm32(R & 31)) : R;
;         voffA[i] = (unsigned)(R * K + C) * 2u; voffB[i] = (unsigned)(Rb * K + C) * 2u; }
;     const size_t kstep = (size_t)(BK * 2);
;     const size_t hstep = (size_t)HALF * K * 2;
;     const size_t tstep = 2 * hstep;
;     const unsigned ldsw = (unsigned)wid * 1024u;
;     const int aoff = lds_byte(wr * 64 + fr, fq * 8), boff = lds_byte(wc * 32 + fr, fq * 8);
;     ...
;     Unit cur, nxt; int ui = 0;
;     if (!S.next(0, cur)) return;
;     f32x4 acc[2][2][4][2];
; #pragma unroll
;     for (int a = 0; a < 2; ++a)
; #pragma unroll
;         for (int b = 0; b < 2; ++b)
; #pragma unroll
;             for (int m = 0; m < 4; ++m)
; #pragma unroll
;                 for (int n = 0; n < 2; ++n) acc[a][b][m][n] = (f32x4){0.f, 0.f, 0.f, 0.f};
;     bf16x8 At[4][2], B0[2][2], B1[2][2];
;     const char* cA = (const char*)g.A + (size_t)cur.pm * tstep + (size_t)cur.koff * 2; const char* cB = (const char*)g.Bt + (size_t)cur.pn * tstep + (size_t)cur.koff * 2;
;     PG8_STAGE(PG8_SB(0, 0), cB, voffB); PG8_STAGE(PG8_SA(0, 0), cA, voffA); PG8_STAGE(PG8_SB(0, 1), cB + hstep, voffB); PG8_STAGE(PG8_SA(0, 1), cA + hstep, voffA);
;     if (wr == 1) PG8_BAR;
;     PG8_WAIT_V(4); PG8_BAR;
;     PG8_STAGE(PG8_SB(1, 0), cB + kstep, voffB); PG8_STAGE(PG8_SA(1, 0), cA + kstep, voffA); PG8_STAGE(PG8_SB(1, 1), cB + hstep + kstep, voffB);
;     PG8_WAIT_V(6); PG8_BAR;
.LBB0_117:
.LBB0_118:
	s_cmp_lt_i32 s80, 2
	s_cselect_b64 s[4:5], -1, 0
	s_and_b64 s[0:1], s[4:5], s[0:1]
	s_add_u32 s86, s78, 0x1d480000
	s_addc_u32 s87, s79, 0
	s_ashr_i32 s85, s2, 31
	s_lshr_b32 s6, s85, 29
	v_writelane_b32 v238, s14, 22
	s_add_i32 s6, s2, s6
	s_ashr_i32 s7, s6, 3
	v_writelane_b32 v238, s15, 23
	s_and_b32 s6, s6, -8
	v_writelane_b32 v238, s7, 24
	s_sub_i32 s6, s2, s6
	v_writelane_b32 v238, s6, 25
	s_andn2_b64 vcc, exec, s[0:1]
	s_ashr_i32 s0, s94, 31
	v_writelane_b32 v238, s0, 26
	s_cbranch_vccnz .LBB0_135
	v_mov_b32_e32 v10, v1
	s_cmpk_gt_i32 s2, 0x483
	s_nop 0
	v_readfirstlane_b32 s12, v10
	s_cbranch_scc1 .LBB0_135
	v_lshlrev_b32_e32 v2, 4, v10
	v_add_u32_e32 v3, 0x2000, v2
	v_ashrrev_i32_e32 v4, 31, v3
	v_lshrrev_b32_e32 v4, 22, v4
	v_add_u32_e32 v4, v3, v4
	v_ashrrev_i32_e32 v11, 10, v4
	v_mul_i32_i24_e32 v4, 0x400, v11
	v_sub_u32_e32 v3, v3, v4
	v_lshrrev_b32_e32 v4, 4, v3
	v_bitop3_b32 v3, v4, v3, 32 bitop3:0x6c
	v_ashrrev_i32_e32 v4, 31, v3
	v_lshrrev_b32_e32 v4, 26, v4
	v_add_u32_e32 v4, v3, v4
	v_lshlrev_b32_e32 v5, 3, v11
	v_ashrrev_i32_e32 v12, 6, v4
	v_and_b32_e32 v5, -16, v5
	v_add_u32_e32 v5, v12, v5
	v_and_b32_e32 v6, 3, v12
	s_mov_b32 s8, 0x1fffe0
	v_lshrrev_b32_e32 v7, 2, v5
	v_lshlrev_b32_e32 v8, 1, v5
	v_and_b32_e32 v4, 0xc0, v4
	v_and_or_b32 v6, v5, s8, v6
	v_and_b32_e32 v7, 4, v7
	v_and_b32_e32 v8, 24, v8
	v_sub_u32_e32 v3, v3, v4
	v_mov_b32_e32 v4, 1
	v_or3_b32 v6, v6, v7, v8
	v_lshlrev_b32_e32 v7, 5, v11
	v_ashrrev_i16_sdwa v3, v4, sext(v3) dst_sel:DWORD dst_unused:UNUSED_PAD src0_sel:DWORD src1_sel:BYTE_0
	v_and_b32_e32 v7, 32, v7
	v_bfe_i32 v13, v3, 0, 16
	v_add_lshl_u32 v3, v7, v13, 1
	v_lshl_add_u32 v130, v6, 11, v3
	v_and_b32_e32 v240, 0x30000, v130
	v_add_u32_e32 v130, v130, v240
	v_lshl_add_u32 v132, v5, 11, v3
	v_bfe_i32 v3, v10, 27, 1
	v_lshrrev_b32_e32 v3, 22, v3
	v_add_u32_e32 v3, v2, v3
	v_and_b32_e32 v3, 0xfffffc00, v3
	v_sub_u32_e32 v2, v2, v3
	v_lshrrev_b32_e32 v3, 4, v2
	v_bitop3_b32 v3, v3, v2, 32 bitop3:0x6c
	v_ashrrev_i32_e32 v2, 31, v2
	v_lshrrev_b32_e32 v2, 26, v2
	v_add_u32_e32 v2, v3, v2
	v_ashrrev_i32_e32 v14, 6, v2
	v_ashrrev_i32_e32 v2, 31, v10
	v_lshrrev_b32_e32 v2, 26, v2
	v_readlane_b32 s7, v238, 25
	v_add_u32_e32 v2, v10, v2
	s_ashr_i32 s6, s12, 6
	s_mul_i32 s0, s7, 0x90
	v_ashrrev_i32_e32 v15, 6, v2
	s_ashr_i32 s1, s12, 8
	s_lshl_b32 s13, s6, 10
	s_or_b32 s0, s0, 4
	v_lshlrev_b32_e32 v2, 3, v15
	s_cmp_lt_i32 s7, 4
	s_mulk_i32 s7, 0x91
	v_and_b32_e32 v2, -16, v2
	v_add_u32_e32 v2, v14, v2
	s_cselect_b32 s0, s7, s0
	v_readlane_b32 s7, v238, 24
	v_and_b32_e32 v5, 3, v14
	v_lshrrev_b32_e32 v6, 2, v2
	v_lshlrev_b32_e32 v7, 1, v2
	s_add_i32 s0, s0, s7
	v_and_or_b32 v5, v2, s8, v5
	v_and_b32_e32 v6, 4, v6
	v_and_b32_e32 v7, 24, v7
	s_mul_hi_i32 s7, s0, 0x78787879
	v_or3_b32 v5, v5, v6, v7
	v_mul_i32_i24_e32 v7, 64, v14
	s_lshr_b32 s8, s7, 31
	s_ashr_i32 s7, s7, 6
	v_sub_u32_e32 v3, v3, v7
	s_add_i32 s7, s7, s8
	v_lshlrev_b32_e32 v6, 5, v15
	v_ashrrev_i16_sdwa v3, v4, sext(v3) dst_sel:DWORD dst_unused:UNUSED_PAD src0_sel:DWORD src1_sel:BYTE_0
	s_lshl_b32 s10, s7, 3
	v_and_b32_e32 v6, 32, v6
	v_bfe_i32 v16, v3, 0, 16
	s_sub_i32 s8, 0x44, s10
	v_add_lshl_u32 v3, v6, v16, 1
	s_min_u32 s11, s8, 8
	s_mulk_i32 s7, 0x88
	v_lshl_add_u32 v134, v5, 11, v3
	v_and_b32_e32 v240, 0x30000, v134
	v_add_u32_e32 v134, v134, v240
	s_sub_i32 s7, s0, s7
	v_cvt_f32_ubyte0_e32 v5, s11
	v_cvt_f32_i32_e32 v4, s7
	v_rcp_iflag_f32_e32 v6, v5
	v_lshl_add_u32 v136, v2, 11, v3
	s_ashr_i32 s0, s7, 30
	s_or_b32 s0, s0, 1
	v_mul_f32_e32 v2, v4, v6
	v_trunc_f32_e32 v2, v2
	v_fma_f32 v3, -v2, v5, v4
	v_cvt_i32_f32_e32 v2, v2
	v_cmp_ge_f32_e64 s[8:9], |v3|, v5
	s_and_b64 s[8:9], s[8:9], exec
	s_cselect_b32 s0, s0, 0
	v_readfirstlane_b32 s8, v2
	s_add_i32 s0, s8, s0
	s_mul_i32 s8, s0, s11
	s_sub_i32 s7, s7, s8
	s_sext_i32_i16 s7, s7
	s_add_i32 s8, s10, s7
	s_ashr_i32 s9, s8, 31
	s_bfe_i64 s[18:19], s[0:1], 0x100000
	s_lshl_b64 s[10:11], s[8:9], 19
	s_lshl_b64 s[18:19], s[18:19], 19
	s_add_u32 s26, s78, s18
	s_addc_u32 s27, s79, s19
	s_add_i32 s9, s13, 0
	s_add_i32 m0, s9, 0x10000
	v_readlane_b32 s14, v238, 20
	global_load_lds_dwordx4 v134, s[26:27]
	s_add_i32 m0, s9, 0x12000
	v_readlane_b32 s15, v238, 21
	s_add_u32 s24, s14, s10
	global_load_lds_dwordx4 v130, s[26:27]
	s_addc_u32 s25, s15, s11
	s_mov_b32 m0, s9
	s_add_i32 s30, s9, 0x2000
	global_load_lds_dwordx4 v136, s[24:25]
	s_mov_b32 m0, s30
	s_add_u32 s10, s26, 0x10000
	global_load_lds_dwordx4 v132, s[24:25]
	s_addc_u32 s11, s27, 0
	s_add_i32 m0, s9, 0x14000
	v_mov_b32_e32 v135, 0
	global_load_lds_dwordx4 v134, s[10:11]
	s_add_i32 m0, s9, 0x16000
	v_mov_b32_e32 v131, v135
	global_load_lds_dwordx4 v130, s[10:11]
	s_add_u32 s10, s24, 0x40000
	s_addc_u32 s11, s25, 0
	s_add_i32 s31, s9, 0x4000
	s_mov_b32 m0, s31
	s_add_i32 s33, s9, 0x6000
	global_load_lds_dwordx4 v136, s[10:11]
	s_mov_b32 m0, s33
	v_mov_b32_e32 v137, v135
	global_load_lds_dwordx4 v132, s[10:11]
	v_mov_b32_e32 v133, v135
	s_mov_b32 s34, 0
	v_lshl_add_u64 v[8:9], s[26:27], 0, v[134:135]
	v_lshl_add_u64 v[6:7], s[26:27], 0, v[130:131]
	v_lshl_add_u64 v[4:5], s[24:25], 0, v[136:137]
	s_cmp_lg_u32 s1, 1
	v_lshl_add_u64 v[2:3], s[24:25], 0, v[132:133]
	s_cbranch_scc1 .LBB0_122
	s_barrier
; #define PG8_STAGE(bufoff, gbase, voff) do { _Pragma("unroll") for (int _i = 0; _i < 2; ++_i) \
;         __builtin_amdgcn_global_load_lds((const unsigned*)((const char*)(gbase) + (voff)[_i]), (LAS unsigned*)(lds + (bufoff) + ldsw + _i * 8192), 16, 0, 0); } while (0)
; #define PG8_WAIT_V(n) asm volatile("s_waitcnt vmcnt(" #n ")" ::: "memory")
; #define PG8_BAR __builtin_amdgcn_s_barrier()
;     DI void operator()(const f32x4 (&acc)[2][2][4][2], const Unit& u, int wr, int wc, int fr, int fq) const {
;         const int row0 = u.pm * BM + wr * 64 + fr, col0 = u.pn * BM + wc * 32 + 8 * fq;
; template <class Epi, class Sched>
; DI void gemm_phase(LAS unsigned char* lds, const Gemm g, const Sched& S, const Epi& E) {
;     ...
;     PG8_STAGE(PG8_SB(0, 0), cB, voffB); PG8_STAGE(PG8_SA(0, 0), cA, voffA); PG8_STAGE(PG8_SB(0, 1), cB + hstep, voffB); PG8_STAGE(PG8_SA(0, 1), cA + hstep, voffA);
;     if (wr == 1) PG8_BAR;
;     PG8_WAIT_V(4); PG8_BAR;
;     PG8_STAGE(PG8_SB(1, 0), cB + kstep, voffB); PG8_STAGE(PG8_SA(1, 0), cA + kstep, voffA); PG8_STAGE(PG8_SB(1, 1), cB + hstep + kstep, voffB);
;     PG8_WAIT_V(6); PG8_BAR;
.LBB0_122:
	s_lshl_b32 s6, s6, 5
	s_and_b32 s19, s6, 0x60
	s_mov_b64 s[6:7], 0x80
	s_add_i32 m0, s9, 0x18000
	v_lshl_add_u64 v[8:9], v[8:9], 0, s[6:7]
	s_lshl_b32 s18, s1, 13
	s_lshl_b32 s20, s19, 7
	s_waitcnt vmcnt(4)
	s_barrier
	global_load_lds_dwordx4 v[8:9], off
	v_lshl_add_u64 v[6:7], v[6:7], 0, s[6:7]
	s_add_i32 m0, s9, 0x1a000
	s_add_i32 s35, s9, 0x8000
	s_add_i32 s36, s9, 0xa000
	global_load_lds_dwordx4 v[6:7], off
	v_lshl_add_u64 v[4:5], v[4:5], 0, s[6:7]
	s_mov_b32 m0, s35
	s_add_u32 s10, s26, 0x10080
	global_load_lds_dwordx4 v[4:5], off
	v_lshl_add_u64 v[2:3], v[2:3], 0, s[6:7]
	s_mov_b32 m0, s36
	s_addc_u32 s11, s27, 0
	global_load_lds_dwordx4 v[2:3], off
	s_add_i32 m0, s9, 0x1c000
	v_lshl_add_u64 v[2:3], s[10:11], 0, v[134:135]
	global_load_lds_dwordx4 v[2:3], off
	v_lshl_add_u64 v[2:3], s[10:11], 0, v[130:131]
	s_add_i32 m0, s9, 0x1e000
	s_add_i32 s37, 0, 0x10000
	global_load_lds_dwordx4 v[2:3], off
	v_lshrrev_b32_e32 v3, 1, v10
	v_and_b32_e32 v3, 24, v3
	v_and_b32_e32 v2, 15, v10
	v_lshlrev_b32_e32 v4, 1, v3
	v_lshl_or_b32 v146, s1, 6, v2
	v_lshl_or_b32 v2, v2, 6, v4
	v_lshlrev_b32_e32 v4, 2, v10
	v_and_b32_e32 v4, 32, v4
	v_bitop3_b32 v5, v2, s18, v4 bitop3:0xde
	v_bitop3_b32 v147, v2, s20, v4 bitop3:0xde
	v_lshlrev_b32_e32 v2, 14, v15
	v_and_b32_e32 v2, 0xffff8000, v2
	v_lshl_or_b32 v148, s19, 1, v3
	v_lshl_add_u32 v2, v14, 11, v2
	v_and_b32_e32 v3, 1, v15
	v_lshl_or_b32 v2, v3, 6, v2
	v_lshl_add_u32 v138, v16, 1, v2
	v_lshlrev_b32_e32 v2, 14, v11
	v_and_b32_e32 v2, 0xffff8000, v2
	s_waitcnt vmcnt(6)
	v_lshl_add_u32 v2, v12, 11, v2
	v_and_b32_e32 v3, 1, v11
	v_lshl_or_b32 v2, v3, 6, v2
	s_add_i32 s38, 0, 0x14000
	s_sext_i32_i16 s40, s0
	v_mov_b32_e32 v139, v135
	v_lshl_add_u32 v140, v13, 1, v2
	v_mov_b32_e32 v141, v135
	v_mov_b64_e32 v[142:143], 0x484
	v_mov_b64_e32 v[144:145], 0x483
	v_add_u32_e32 v149, s37, v147
	v_add_u32_e32 v150, 0, v5
	v_add_u32_e32 v151, s38, v147
	s_movk_i32 s39, 0x2200
	s_barrier

; #define PG8_STAGE(bufoff, gbase, voff) do { _Pragma("unroll") for (int _i = 0; _i < 2; ++_i) \
;         __builtin_amdgcn_global_load_lds((const unsigned*)((const char*)(gbase) + (voff)[_i]), (LAS unsigned*)(lds + (bufoff) + ldsw + _i * 8192), 16, 0, 0); } while (0)
; #define PG8_LDA(dst, b, h) do { _Pragma("unroll") for (int m = 0; m < 4; ++m) _Pragma("unroll") for (int k = 0; k < 2; ++k) dst[m][k] = *(const LAS bf16x8*)(lds + PG8_SA(b, h) + aoff + m * 2048 + k * 1024); } while (0)
; #define PG8_LDB(dst, b, h) do { _Pragma("unroll") for (int n = 0; n < 2; ++n) _Pragma("unroll") for (int k = 0; k < 2; ++k) dst[n][k] = *(const LAS bf16x8*)(lds + PG8_SB(b, h) + boff + n * 2048 + k * 1024); } while (0)
; #define PG8_MMA(ai, bj, At, Bt) do { __builtin_amdgcn_s_setprio(1); _Pragma("unroll") for (int m = 0; m < 4; ++m) _Pragma("unroll") for (int n = 0; n < 2; ++n) _Pragma("unroll") for (int k = 0; k < 2; ++k) \
;         acc[ai][bj][m][n] = __builtin_amdgcn_mfma_f32_16x16x32_bf16(Bt[n][k], At[m][k], acc[ai][bj][m][n], 0, 0, 0); __builtin_amdgcn_s_setprio(0); } while (0)
; #define PG8_WAIT_V(n) asm volatile("s_waitcnt vmcnt(" #n ")" ::: "memory")
; #define PG8_WAIT_L(n) asm volatile("s_waitcnt lgkmcnt(" #n ")" ::: "memory")
; #define PG8_BAR __builtin_amdgcn_s_barrier()
; #define PG8_SCHED __builtin_amdgcn_sched_barrier(0)
; template <class Epi, class Sched>
; DI void gemm_phase(LAS unsigned char* lds, const Gemm g, const Sched& S, const Epi& E) {
;     ...
;             PG8_LDB(B0, 0, 0); PG8_SCHED; PG8_LDA(At, 0, 0); PG8_STAGE(PG8_SA(1, 1), a1 + hstep, voffA);
;             PG8_WAIT_L(8); PG8_BAR; PG8_WAIT_L(0); PG8_MMA(0, 0, At, B0); PG8_BAR; PG8_SCHED;
;             PG8_LDB(B1, 0, 1); PG8_STAGE(PG8_SB(0, 0), b2, voffB);
;             PG8_BAR; PG8_WAIT_L(0); PG8_MMA(0, 1, At, B1); PG8_BAR;
;             PG8_LDA(At, 0, 1); PG8_STAGE(PG8_SA(0, 0), a2, voffA);
;             PG8_BAR; PG8_WAIT_L(0); PG8_MMA(1, 0, At, B0); PG8_BAR; PG8_SCHED;
;             PG8_STAGE(PG8_SB(0, 1), b2 + hstep, voffB);
;             PG8_WAIT_V(6); PG8_BAR; PG8_MMA(1, 1, At, B1); PG8_BAR;
.LBB0_130:
	ds_read_b128 v[156:159], v149
	ds_read_b128 v[160:163], v149 offset:1024
	ds_read_b128 v[164:167], v149 offset:2048
	ds_read_b128 v[168:171], v149 offset:3072
	s_add_u32 s26, s24, 0xfffc0080
	s_addc_u32 s27, s25, -1
	s_cmp_eq_u32 s45, 12
	s_cselect_b32 s29, s19, s27
	s_cselect_b32 s28, s41, s26
	s_cselect_b32 s27, s11, s44
	s_cselect_b32 s26, s42, s43
	v_lshl_add_u64 v[204:205], s[24:25], 0, v[138:139]
	s_add_i32 m0, s9, 0xc000
	ds_read_b128 v[172:175], v150
	ds_read_b128 v[176:179], v150 offset:1024
	ds_read_b128 v[180:183], v150 offset:2048
	ds_read_b128 v[184:187], v150 offset:3072
	ds_read_b128 v[188:191], v150 offset:4096
	ds_read_b128 v[192:195], v150 offset:5120
	ds_read_b128 v[196:199], v150 offset:6144
	ds_read_b128 v[200:203], v150 offset:7168
	global_load_lds_dwordx4 v[204:205], off
	v_lshl_add_u64 v[204:205], s[24:25], 0, v[140:141]
	s_add_i32 m0, s9, 0xe000
	s_nop 0
	global_load_lds_dwordx4 v[204:205], off
	s_waitcnt lgkmcnt(8)
	s_barrier
	s_waitcnt lgkmcnt(0)
	s_setprio 1
	s_waitcnt lgkmcnt(0)
	v_mfma_f32_16x16x32_bf16 v[126:129], v[156:159], v[172:175], v[126:129]
	v_mfma_f32_16x16x32_bf16 v[122:125], v[164:167], v[172:175], v[122:125]
	v_mfma_f32_16x16x32_bf16 v[118:121], v[156:159], v[180:183], v[118:121]
	v_mfma_f32_16x16x32_bf16 v[114:117], v[164:167], v[180:183], v[114:117]
	v_mfma_f32_16x16x32_bf16 v[102:105], v[156:159], v[188:191], v[102:105]
	v_mfma_f32_16x16x32_bf16 v[98:101], v[164:167], v[188:191], v[98:101]
	v_mfma_f32_16x16x32_bf16 v[86:89], v[156:159], v[196:199], v[86:89]
	v_mfma_f32_16x16x32_bf16 v[82:85], v[164:167], v[196:199], v[82:85]
	v_mfma_f32_16x16x32_bf16 v[126:129], v[160:163], v[176:179], v[126:129]
	v_mfma_f32_16x16x32_bf16 v[122:125], v[168:171], v[176:179], v[122:125]
	v_mfma_f32_16x16x32_bf16 v[118:121], v[160:163], v[184:187], v[118:121]
	v_mfma_f32_16x16x32_bf16 v[114:117], v[168:171], v[184:187], v[114:117]
	v_mfma_f32_16x16x32_bf16 v[102:105], v[160:163], v[192:195], v[102:105]
	v_mfma_f32_16x16x32_bf16 v[98:101], v[168:171], v[192:195], v[98:101]
	v_mfma_f32_16x16x32_bf16 v[86:89], v[160:163], v[200:203], v[86:89]
	v_mfma_f32_16x16x32_bf16 v[82:85], v[168:171], v[200:203], v[82:85]
	s_setprio 0
	s_barrier
	s_add_i32 s46, s37, s13
	v_lshl_add_u64 v[220:221], s[26:27], 0, v[134:135]
	s_mov_b32 m0, s46
	ds_read_b128 v[204:207], v151
	ds_read_b128 v[208:211], v151 offset:1024
	ds_read_b128 v[212:215], v151 offset:2048
	ds_read_b128 v[216:219], v151 offset:3072
	global_load_lds_dwordx4 v[220:221], off
	v_lshl_add_u64 v[222:223], s[26:27], 0, v[130:131]
	s_add_i32 m0, s46, 0x2000
	s_nop 0
	global_load_lds_dwordx4 v[222:223], off
	s_barrier
	s_waitcnt lgkmcnt(0)
	s_setprio 1
	s_waitcnt lgkmcnt(0)
	v_mfma_f32_16x16x32_bf16 v[110:113], v[204:207], v[172:175], v[110:113]
	v_mfma_f32_16x16x32_bf16 v[106:109], v[212:215], v[172:175], v[106:109]
	v_mfma_f32_16x16x32_bf16 v[94:97], v[204:207], v[180:183], v[94:97]
	v_mfma_f32_16x16x32_bf16 v[90:93], v[212:215], v[180:183], v[90:93]
	v_mfma_f32_16x16x32_bf16 v[78:81], v[204:207], v[188:191], v[78:81]
	v_mfma_f32_16x16x32_bf16 v[74:77], v[212:215], v[188:191], v[74:77]
	v_mfma_f32_16x16x32_bf16 v[70:73], v[204:207], v[196:199], v[70:73]
	v_mfma_f32_16x16x32_bf16 v[66:69], v[212:215], v[196:199], v[66:69]
	v_mfma_f32_16x16x32_bf16 v[110:113], v[208:211], v[176:179], v[110:113]
	v_mfma_f32_16x16x32_bf16 v[106:109], v[216:219], v[176:179], v[106:109]
	v_mfma_f32_16x16x32_bf16 v[94:97], v[208:211], v[184:187], v[94:97]
	v_mfma_f32_16x16x32_bf16 v[90:93], v[216:219], v[184:187], v[90:93]
	v_mfma_f32_16x16x32_bf16 v[78:81], v[208:211], v[192:195], v[78:81]
	v_mfma_f32_16x16x32_bf16 v[74:77], v[216:219], v[192:195], v[74:77]
	v_mfma_f32_16x16x32_bf16 v[70:73], v[208:211], v[200:203], v[70:73]
	v_mfma_f32_16x16x32_bf16 v[66:69], v[216:219], v[200:203], v[66:69]
	s_setprio 0
	s_mov_b32 m0, s9
	v_lshl_add_u64 v[224:225], s[28:29], 0, v[136:137]
	s_barrier
	ds_read_b128 v[172:175], v150 offset:16384
	ds_read_b128 v[176:179], v150 offset:17408
	ds_read_b128 v[180:183], v150 offset:18432
	ds_read_b128 v[184:187], v150 offset:19456
	ds_read_b128 v[188:191], v150 offset:20480
	ds_read_b128 v[192:195], v150 offset:21504
	ds_read_b128 v[196:199], v150 offset:22528
	ds_read_b128 v[200:203], v150 offset:23552
	global_load_lds_dwordx4 v[224:225], off
	v_lshl_add_u64 v[226:227], s[28:29], 0, v[132:133]
	s_mov_b32 m0, s30
	s_nop 0
	global_load_lds_dwordx4 v[226:227], off
	s_barrier
	s_waitcnt lgkmcnt(0)
	s_setprio 1
	s_waitcnt lgkmcnt(0)
	v_mfma_f32_16x16x32_bf16 v[62:65], v[156:159], v[172:175], v[62:65]
	v_mfma_f32_16x16x32_bf16 v[58:61], v[164:167], v[172:175], v[58:61]
	v_mfma_f32_16x16x32_bf16 v[54:57], v[156:159], v[180:183], v[54:57]
	v_mfma_f32_16x16x32_bf16 v[50:53], v[164:167], v[180:183], v[50:53]
	v_mfma_f32_16x16x32_bf16 v[38:41], v[156:159], v[188:191], v[38:41]
	v_mfma_f32_16x16x32_bf16 v[34:37], v[164:167], v[188:191], v[34:37]
	v_mfma_f32_16x16x32_bf16 v[22:25], v[156:159], v[196:199], v[22:25]
	v_mfma_f32_16x16x32_bf16 v[18:21], v[164:167], v[196:199], v[18:21]
	v_mfma_f32_16x16x32_bf16 v[62:65], v[160:163], v[176:179], v[62:65]
	v_mfma_f32_16x16x32_bf16 v[58:61], v[168:171], v[176:179], v[58:61]
	v_mfma_f32_16x16x32_bf16 v[54:57], v[160:163], v[184:187], v[54:57]
	v_mfma_f32_16x16x32_bf16 v[50:53], v[168:171], v[184:187], v[50:53]
	v_mfma_f32_16x16x32_bf16 v[38:41], v[160:163], v[192:195], v[38:41]
	v_mfma_f32_16x16x32_bf16 v[34:37], v[168:171], v[192:195], v[34:37]
	v_mfma_f32_16x16x32_bf16 v[22:25], v[160:163], v[200:203], v[22:25]
	v_mfma_f32_16x16x32_bf16 v[18:21], v[168:171], v[200:203], v[18:21]
	s_setprio 0
	s_barrier
; #define PG8_STAGE(bufoff, gbase, voff) do { _Pragma("unroll") for (int _i = 0; _i < 2; ++_i) \
;         __builtin_amdgcn_global_load_lds((const unsigned*)((const char*)(gbase) + (voff)[_i]), (LAS unsigned*)(lds + (bufoff) + ldsw + _i * 8192), 16, 0, 0); } while (0)
; #define PG8_LDA(dst, b, h) do { _Pragma("unroll") for (int m = 0; m < 4; ++m) _Pragma("unroll") for (int k = 0; k < 2; ++k) dst[m][k] = *(const LAS bf16x8*)(lds + PG8_SA(b, h) + aoff + m * 2048 + k * 1024); } while (0)
; #define PG8_LDB(dst, b, h) do { _Pragma("unroll") for (int n = 0; n < 2; ++n) _Pragma("unroll") for (int k = 0; k < 2; ++k) dst[n][k] = *(const LAS bf16x8*)(lds + PG8_SB(b, h) + boff + n * 2048 + k * 1024); } while (0)
; #define PG8_MMA(ai, bj, At, Bt) do { __builtin_amdgcn_s_setprio(1); _Pragma("unroll") for (int m = 0; m < 4; ++m) _Pragma("unroll") for (int n = 0; n < 2; ++n) _Pragma("unroll") for (int k = 0; k < 2; ++k) \
;         acc[ai][bj][m][n] = __builtin_amdgcn_mfma_f32_16x16x32_bf16(Bt[n][k], At[m][k], acc[ai][bj][m][n], 0, 0, 0); __builtin_amdgcn_s_setprio(0); } while (0)
; #define PG8_WAIT_V(n) asm volatile("s_waitcnt vmcnt(" #n ")" ::: "memory")
; #define PG8_WAIT_L(n) asm volatile("s_waitcnt lgkmcnt(" #n ")" ::: "memory")
; #define PG8_BAR __builtin_amdgcn_s_barrier()
; #define PG8_SCHED __builtin_amdgcn_sched_barrier(0)
; template <class Epi, class Sched>
; DI void gemm_phase(LAS unsigned char* lds, const Gemm g, const Sched& S, const Epi& E) {
;     ...
;             PG8_STAGE(PG8_SB(0, 1), b2 + hstep, voffB);
;             PG8_WAIT_V(6); PG8_BAR; PG8_MMA(1, 1, At, B1); PG8_BAR;
;             PG8_LDB(B0, 1, 0); PG8_SCHED; PG8_LDA(At, 1, 0); PG8_STAGE(PG8_SA(0, 1), a2 + hstep, voffA);
;             PG8_WAIT_L(8); PG8_BAR; PG8_WAIT_L(0); PG8_MMA(0, 0, At, B0); PG8_BAR; PG8_SCHED;
;             PG8_LDB(B1, 1, 1); PG8_STAGE(PG8_SB(1, 0), b3, voffB);
;             PG8_BAR; PG8_WAIT_L(0); PG8_MMA(0, 1, At, B1); PG8_BAR;
;             PG8_LDA(At, 1, 1); PG8_STAGE(PG8_SA(1, 0), a3, voffA);
;             PG8_BAR; PG8_WAIT_L(0); PG8_MMA(1, 0, At, B0); PG8_BAR; PG8_SCHED;
	s_add_u32 s46, s26, 0x10000
	s_addc_u32 s47, s27, 0
	s_add_i32 s48, s38, s13
	v_lshl_add_u64 v[156:157], s[46:47], 0, v[134:135]
	s_mov_b32 m0, s48
	s_nop 0
	global_load_lds_dwordx4 v[156:157], off
	v_lshl_add_u64 v[156:157], s[46:47], 0, v[130:131]
	s_add_i32 m0, s48, 0x2000
	s_nop 0
	global_load_lds_dwordx4 v[156:157], off
	s_waitcnt vmcnt(6)
	s_barrier
	s_setprio 1
	v_mfma_f32_16x16x32_bf16 v[46:49], v[204:207], v[172:175], v[46:49]
	v_mfma_f32_16x16x32_bf16 v[42:45], v[212:215], v[172:175], v[42:45]
	v_mfma_f32_16x16x32_bf16 v[30:33], v[204:207], v[180:183], v[30:33]
	v_mfma_f32_16x16x32_bf16 v[26:29], v[212:215], v[180:183], v[26:29]
	v_mfma_f32_16x16x32_bf16 v[14:17], v[204:207], v[188:191], v[14:17]
	v_mfma_f32_16x16x32_bf16 v[10:13], v[212:215], v[188:191], v[10:13]
	v_mfma_f32_16x16x32_bf16 v[6:9], v[204:207], v[196:199], v[6:9]
	v_mfma_f32_16x16x32_bf16 v[2:5], v[212:215], v[196:199], v[2:5]
	v_mfma_f32_16x16x32_bf16 v[46:49], v[208:211], v[176:179], v[46:49]
	v_mfma_f32_16x16x32_bf16 v[42:45], v[216:219], v[176:179], v[42:45]
	v_mfma_f32_16x16x32_bf16 v[30:33], v[208:211], v[184:187], v[30:33]
	v_mfma_f32_16x16x32_bf16 v[26:29], v[216:219], v[184:187], v[26:29]
	v_mfma_f32_16x16x32_bf16 v[14:17], v[208:211], v[192:195], v[14:17]
	v_mfma_f32_16x16x32_bf16 v[10:13], v[216:219], v[192:195], v[10:13]
	v_mfma_f32_16x16x32_bf16 v[6:9], v[208:211], v[200:203], v[6:9]
	v_mfma_f32_16x16x32_bf16 v[2:5], v[216:219], v[200:203], v[2:5]
	s_setprio 0
	s_add_i32 s46, 0, 0x18000
	v_add_u32_e32 v154, s46, v147
	s_barrier
	ds_read_b128 v[156:159], v154
	ds_read_b128 v[160:163], v154 offset:1024
	ds_read_b128 v[164:167], v154 offset:2048
	ds_read_b128 v[168:171], v154 offset:3072
	s_add_u32 s28, s28, 0x40000
	s_addc_u32 s29, s29, 0
	s_mov_b32 m0, s31
	v_lshl_add_u64 v[204:205], s[28:29], 0, v[136:137]
	ds_read_b128 v[172:175], v150 offset:32768
	ds_read_b128 v[176:179], v150 offset:33792
	ds_read_b128 v[180:183], v150 offset:34816
	ds_read_b128 v[184:187], v150 offset:35840
	ds_read_b128 v[188:191], v150 offset:36864
	ds_read_b128 v[192:195], v150 offset:37888
	ds_read_b128 v[196:199], v150 offset:38912
	ds_read_b128 v[200:203], v150 offset:39936
	global_load_lds_dwordx4 v[204:205], off
	v_lshl_add_u64 v[204:205], s[28:29], 0, v[132:133]
	s_mov_b32 m0, s33
	s_nop 0
	global_load_lds_dwordx4 v[204:205], off
	s_waitcnt lgkmcnt(8)
	s_barrier
	s_waitcnt lgkmcnt(0)
	s_setprio 1
	s_waitcnt lgkmcnt(0)
	v_mfma_f32_16x16x32_bf16 v[126:129], v[156:159], v[172:175], v[126:129]
	v_mfma_f32_16x16x32_bf16 v[122:125], v[164:167], v[172:175], v[122:125]
	v_mfma_f32_16x16x32_bf16 v[118:121], v[156:159], v[180:183], v[118:121]
	v_mfma_f32_16x16x32_bf16 v[114:117], v[164:167], v[180:183], v[114:117]
	v_mfma_f32_16x16x32_bf16 v[102:105], v[156:159], v[188:191], v[102:105]
	v_mfma_f32_16x16x32_bf16 v[98:101], v[164:167], v[188:191], v[98:101]
	v_mfma_f32_16x16x32_bf16 v[86:89], v[156:159], v[196:199], v[86:89]
	v_mfma_f32_16x16x32_bf16 v[82:85], v[164:167], v[196:199], v[82:85]
	v_mfma_f32_16x16x32_bf16 v[126:129], v[160:163], v[176:179], v[126:129]
	v_mfma_f32_16x16x32_bf16 v[122:125], v[168:171], v[176:179], v[122:125]
	v_mfma_f32_16x16x32_bf16 v[118:121], v[160:163], v[184:187], v[118:121]
	v_mfma_f32_16x16x32_bf16 v[114:117], v[168:171], v[184:187], v[114:117]
	v_mfma_f32_16x16x32_bf16 v[102:105], v[160:163], v[192:195], v[102:105]
	v_mfma_f32_16x16x32_bf16 v[98:101], v[168:171], v[192:195], v[98:101]
	v_mfma_f32_16x16x32_bf16 v[86:89], v[160:163], v[200:203], v[86:89]
	v_mfma_f32_16x16x32_bf16 v[82:85], v[168:171], v[200:203], v[82:85]
	s_setprio 0
	s_barrier
	s_add_i32 s28, 0, 0x1c000
	s_add_i32 s29, s46, s13
	v_add_u32_e32 v154, s28, v147
	v_lshl_add_u64 v[220:221], v[220:221], 0, s[6:7]
	s_mov_b32 m0, s29
	ds_read_b128 v[204:207], v154
	ds_read_b128 v[208:211], v154 offset:1024
	ds_read_b128 v[212:215], v154 offset:2048
	ds_read_b128 v[216:219], v154 offset:3072
	global_load_lds_dwordx4 v[220:221], off
	v_lshl_add_u64 v[220:221], v[222:223], 0, s[6:7]
	s_add_i32 m0, s29, 0x2000
	s_nop 0
	global_load_lds_dwordx4 v[220:221], off
	s_barrier
	s_waitcnt lgkmcnt(0)
	s_setprio 1
	s_waitcnt lgkmcnt(0)
	v_mfma_f32_16x16x32_bf16 v[110:113], v[204:207], v[172:175], v[110:113]
	v_mfma_f32_16x16x32_bf16 v[106:109], v[212:215], v[172:175], v[106:109]
	v_mfma_f32_16x16x32_bf16 v[94:97], v[204:207], v[180:183], v[94:97]
	v_mfma_f32_16x16x32_bf16 v[90:93], v[212:215], v[180:183], v[90:93]
	v_mfma_f32_16x16x32_bf16 v[78:81], v[204:207], v[188:191], v[78:81]
	v_mfma_f32_16x16x32_bf16 v[74:77], v[212:215], v[188:191], v[74:77]
	v_mfma_f32_16x16x32_bf16 v[70:73], v[204:207], v[196:199], v[70:73]
	v_mfma_f32_16x16x32_bf16 v[66:69], v[212:215], v[196:199], v[66:69]
	v_mfma_f32_16x16x32_bf16 v[110:113], v[208:211], v[176:179], v[110:113]
	v_mfma_f32_16x16x32_bf16 v[106:109], v[216:219], v[176:179], v[106:109]
	v_mfma_f32_16x16x32_bf16 v[94:97], v[208:211], v[184:187], v[94:97]
	v_mfma_f32_16x16x32_bf16 v[90:93], v[216:219], v[184:187], v[90:93]
	v_mfma_f32_16x16x32_bf16 v[78:81], v[208:211], v[192:195], v[78:81]
	v_mfma_f32_16x16x32_bf16 v[74:77], v[216:219], v[192:195], v[74:77]
	v_mfma_f32_16x16x32_bf16 v[70:73], v[208:211], v[200:203], v[70:73]
	v_mfma_f32_16x16x32_bf16 v[66:69], v[216:219], v[200:203], v[66:69]
	s_setprio 0
	s_mov_b32 m0, s35
	v_lshl_add_u64 v[220:221], v[224:225], 0, s[6:7]
	s_barrier
	ds_read_b128 v[172:175], v150 offset:49152
	ds_read_b128 v[176:179], v150 offset:50176
	ds_read_b128 v[180:183], v150 offset:51200
	ds_read_b128 v[184:187], v150 offset:52224
	ds_read_b128 v[188:191], v150 offset:53248
	ds_read_b128 v[192:195], v150 offset:54272
	ds_read_b128 v[196:199], v150 offset:55296
	ds_read_b128 v[200:203], v150 offset:56320
	global_load_lds_dwordx4 v[220:221], off
	v_lshl_add_u64 v[220:221], v[226:227], 0, s[6:7]
	s_mov_b32 m0, s36
	s_nop 0
	global_load_lds_dwordx4 v[220:221], off
	s_barrier
; DI unsigned pk_bf16(float a, float b) { f32x2 v = {a, b}; bf2_t r = __builtin_convertvector(v, bf2_t); return __builtin_bit_cast(unsigned, r); }
; #define PG8_STAGE(bufoff, gbase, voff) do { _Pragma("unroll") for (int _i = 0; _i < 2; ++_i) \
;         __builtin_amdgcn_global_load_lds((const unsigned*)((const char*)(gbase) + (voff)[_i]), (LAS unsigned*)(lds + (bufoff) + ldsw + _i * 8192), 16, 0, 0); } while (0)
; #define PG8_MMA(ai, bj, At, Bt) do { __builtin_amdgcn_s_setprio(1); _Pragma("unroll") for (int m = 0; m < 4; ++m) _Pragma("unroll") for (int n = 0; n < 2; ++n) _Pragma("unroll") for (int k = 0; k < 2; ++k) \
;         acc[ai][bj][m][n] = __builtin_amdgcn_mfma_f32_16x16x32_bf16(Bt[n][k], At[m][k], acc[ai][bj][m][n], 0, 0, 0); __builtin_amdgcn_s_setprio(0); } while (0)
; #define PG8_WAIT_V(n) asm volatile("s_waitcnt vmcnt(" #n ")" ::: "memory")
; #define PG8_WAIT_L(n) asm volatile("s_waitcnt lgkmcnt(" #n ")" ::: "memory")
; #define PG8_BAR __builtin_amdgcn_s_barrier()
; #define PG8_SCHED __builtin_amdgcn_sched_barrier(0)
;     DI void operator()(const f32x4 (&acc)[2][2][4][2], const Unit& u, int wr, int wc, int fr, int fq) const {
;     ...
;             for (int m = 0; m < 4; ++m) { bf16_t* rowp = O + (size_t)(row0 + ai * HALF + m * 16) * ldc + col0;
; #pragma unroll
;                 for (int bj = 0; bj < 2; ++bj) { const f32x4 v0 = acc[ai][bj][m][0], v1 = acc[ai][bj][m][1];
;                     u32x4 w; w.x = pk_bf16(v0[0], v0[1]); w.y = pk_bf16(v0[2], v0[3]); w.z = pk_bf16(v1[0], v1[1]); w.w = pk_bf16(v1[2], v1[3]);
;                     *(u32x4*)(rowp + bj * HALF) = w; } }
; template <class Epi, class Sched>
; DI void gemm_phase(LAS unsigned char* lds, const Gemm g, const Sched& S, const Epi& E) {
;     ...
;             PG8_BAR; PG8_WAIT_L(0); PG8_MMA(1, 0, At, B0); PG8_BAR; PG8_SCHED;
;             PG8_STAGE(PG8_SB(1, 1), b3 + hstep, voffB);
;             PG8_WAIT_V(6); PG8_BAR; PG8_MMA(1, 1, At, B1); PG8_BAR;
	s_waitcnt lgkmcnt(0)
	s_setprio 1
	s_waitcnt lgkmcnt(0)
	v_mfma_f32_16x16x32_bf16 v[62:65], v[156:159], v[172:175], v[62:65]
	v_mfma_f32_16x16x32_bf16 v[58:61], v[164:167], v[172:175], v[58:61]
	v_mfma_f32_16x16x32_bf16 v[54:57], v[156:159], v[180:183], v[54:57]
	v_mfma_f32_16x16x32_bf16 v[50:53], v[164:167], v[180:183], v[50:53]
	v_mfma_f32_16x16x32_bf16 v[38:41], v[156:159], v[188:191], v[38:41]
	v_mfma_f32_16x16x32_bf16 v[34:37], v[164:167], v[188:191], v[34:37]
	v_mfma_f32_16x16x32_bf16 v[22:25], v[156:159], v[196:199], v[22:25]
	v_mfma_f32_16x16x32_bf16 v[18:21], v[164:167], v[196:199], v[18:21]
	v_mfma_f32_16x16x32_bf16 v[62:65], v[160:163], v[176:179], v[62:65]
	v_mfma_f32_16x16x32_bf16 v[58:61], v[168:171], v[176:179], v[58:61]
	v_mfma_f32_16x16x32_bf16 v[54:57], v[160:163], v[184:187], v[54:57]
	v_mfma_f32_16x16x32_bf16 v[50:53], v[168:171], v[184:187], v[50:53]
	v_mfma_f32_16x16x32_bf16 v[38:41], v[160:163], v[192:195], v[38:41]
	v_mfma_f32_16x16x32_bf16 v[34:37], v[168:171], v[192:195], v[34:37]
	v_mfma_f32_16x16x32_bf16 v[22:25], v[160:163], v[200:203], v[22:25]
	v_mfma_f32_16x16x32_bf16 v[18:21], v[168:171], v[200:203], v[18:21]
	s_setprio 0
	s_barrier
	s_add_u32 s26, s26, 0x10080
	s_addc_u32 s27, s27, 0
	s_add_i32 s28, s28, s13
	v_lshl_add_u64 v[156:157], s[26:27], 0, v[134:135]
	s_mov_b32 m0, s28
	s_nop 0
	global_load_lds_dwordx4 v[156:157], off
	v_lshl_add_u64 v[156:157], s[26:27], 0, v[130:131]
	s_add_i32 m0, s28, 0x2000
	s_nop 0
	global_load_lds_dwordx4 v[156:157], off
	s_waitcnt vmcnt(6)
	s_barrier
	s_setprio 1
	v_mfma_f32_16x16x32_bf16 v[46:49], v[204:207], v[172:175], v[46:49]
	v_mfma_f32_16x16x32_bf16 v[42:45], v[212:215], v[172:175], v[42:45]
	v_mfma_f32_16x16x32_bf16 v[30:33], v[204:207], v[180:183], v[30:33]
	v_mfma_f32_16x16x32_bf16 v[26:29], v[212:215], v[180:183], v[26:29]
	v_mfma_f32_16x16x32_bf16 v[14:17], v[204:207], v[188:191], v[14:17]
	v_mfma_f32_16x16x32_bf16 v[10:13], v[212:215], v[188:191], v[10:13]
	v_mfma_f32_16x16x32_bf16 v[6:9], v[204:207], v[196:199], v[6:9]
	v_mfma_f32_16x16x32_bf16 v[2:5], v[212:215], v[196:199], v[2:5]
	v_mfma_f32_16x16x32_bf16 v[46:49], v[208:211], v[176:179], v[46:49]
	v_mfma_f32_16x16x32_bf16 v[42:45], v[216:219], v[176:179], v[42:45]
	v_mfma_f32_16x16x32_bf16 v[30:33], v[208:211], v[184:187], v[30:33]
	v_mfma_f32_16x16x32_bf16 v[26:29], v[216:219], v[184:187], v[26:29]
	v_mfma_f32_16x16x32_bf16 v[14:17], v[208:211], v[192:195], v[14:17]
	v_mfma_f32_16x16x32_bf16 v[10:13], v[216:219], v[192:195], v[10:13]
	v_mfma_f32_16x16x32_bf16 v[6:9], v[208:211], v[200:203], v[6:9]
	v_mfma_f32_16x16x32_bf16 v[2:5], v[216:219], v[200:203], v[2:5]
	s_setprio 0
	s_add_i32 s45, s45, 2
	s_add_u32 s24, s24, 0x100
	s_addc_u32 s25, s25, 0
	s_add_u32 s43, s43, 0x100
	s_addc_u32 s44, s44, 0
	s_cmp_gt_u32 s45, 13
	s_barrier
	s_cbranch_scc0 .LBB0_130
	v_and_b32_e32 v156, 8, v146
	v_sub_u32_e32 v157, v146, v156
	v_lshl_add_u32 v157, s8, 8, v157
	v_lshl_add_u32 v156, v156, 2, v148
	v_lshl_or_b32 v156, s40, 8, v156
	v_mul_u32_u24_e32 v157, 0x2200, v157
	v_lshl_add_u32 v244, v156, 1, v157
	v_add_u32_e32 v245, 0x11000, v244
	v_add_u32_e32 v246, 0x22000, v244
	v_add_u32_e32 v247, 0x33000, v244
	v_add_u32_e32 v248, 0x44000, v244
	v_add_u32_e32 v249, 0x55000, v244
	v_add_u32_e32 v250, 0x66000, v244
	v_add_u32_e32 v251, 0x77000, v244
	v_add_u32_e32 v252, 0x110000, v244
	v_add_u32_e32 v253, 0x121000, v244
	v_add_u32_e32 v254, 0x132000, v244
	v_add_u32_e32 v255, 0x143000, v244
	v_add_u32_e32 v158, 0x154000, v244
	v_add_u32_e32 v159, 0x165000, v244
	v_add_u32_e32 v160, 0x176000, v244
	v_add_u32_e32 v161, 0x187000, v244
	s_and_b64 vcc, exec, s[0:1]
	s_mov_b32 s40, s10
	s_mov_b32 s8, s18
	s_mov_b64 s[26:27], s[22:23]
	s_mov_b64 s[24:25], s[20:21]
	v_cvt_pk_bf16_f32 v126, v126, v127
	v_cvt_pk_bf16_f32 v127, v128, v129
	v_cvt_pk_bf16_f32 v128, v122, v123
	v_cvt_pk_bf16_f32 v129, v124, v125
	v_cvt_pk_bf16_f32 v110, v110, v111
	v_cvt_pk_bf16_f32 v111, v112, v113
	v_cvt_pk_bf16_f32 v112, v106, v107
	v_cvt_pk_bf16_f32 v113, v108, v109
	v_mov_b32_dpp v240, v126 row_ror:8 row_mask:0xf bank_mask:0xf
	v_mov_b32_dpp v241, v127 row_ror:8 row_mask:0xf bank_mask:0xf
	v_mov_b32_dpp v242, v128 row_ror:8 row_mask:0xf bank_mask:0xf
	v_mov_b32_dpp v243, v129 row_ror:8 row_mask:0xf bank_mask:0xf
	v_mov_b32_dpp v126, v110 row_ror:8 row_mask:0xf bank_mask:0xc
	v_mov_b32_dpp v127, v111 row_ror:8 row_mask:0xf bank_mask:0xc
	v_mov_b32_dpp v128, v112 row_ror:8 row_mask:0xf bank_mask:0xc
	v_mov_b32_dpp v129, v113 row_ror:8 row_mask:0xf bank_mask:0xc
	v_mov_b32_dpp v110, v240 quad_perm:[0,1,2,3] row_mask:0xf bank_mask:0x3
	v_mov_b32_dpp v111, v241 quad_perm:[0,1,2,3] row_mask:0xf bank_mask:0x3
	v_mov_b32_dpp v112, v242 quad_perm:[0,1,2,3] row_mask:0xf bank_mask:0x3
	v_mov_b32_dpp v113, v243 quad_perm:[0,1,2,3] row_mask:0xf bank_mask:0x3
	global_store_dwordx4 v244, v[126:129], s[86:87]
	global_store_dwordx4 v245, v[110:113], s[86:87]
	v_cvt_pk_bf16_f32 v118, v118, v119
	v_cvt_pk_bf16_f32 v119, v120, v121
	v_cvt_pk_bf16_f32 v120, v114, v115
	v_cvt_pk_bf16_f32 v121, v116, v117
	v_cvt_pk_bf16_f32 v94, v94, v95
	v_cvt_pk_bf16_f32 v95, v96, v97
	v_cvt_pk_bf16_f32 v96, v90, v91
	v_cvt_pk_bf16_f32 v97, v92, v93
	v_mov_b32_dpp v240, v118 row_ror:8 row_mask:0xf bank_mask:0xf
	v_mov_b32_dpp v241, v119 row_ror:8 row_mask:0xf bank_mask:0xf
	v_mov_b32_dpp v242, v120 row_ror:8 row_mask:0xf bank_mask:0xf
	v_mov_b32_dpp v243, v121 row_ror:8 row_mask:0xf bank_mask:0xf
	v_mov_b32_dpp v118, v94 row_ror:8 row_mask:0xf bank_mask:0xc
	v_mov_b32_dpp v119, v95 row_ror:8 row_mask:0xf bank_mask:0xc
	v_mov_b32_dpp v120, v96 row_ror:8 row_mask:0xf bank_mask:0xc
; DI unsigned pk_bf16(float a, float b) { f32x2 v = {a, b}; bf2_t r = __builtin_convertvector(v, bf2_t); return __builtin_bit_cast(unsigned, r); }
;     DI void operator()(const f32x4 (&acc)[2][2][4][2], const Unit& u, int wr, int wc, int fr, int fq) const {
;     ...
;             for (int m = 0; m < 4; ++m) { bf16_t* rowp = O + (size_t)(row0 + ai * HALF + m * 16) * ldc + col0;
; #pragma unroll
;                 for (int bj = 0; bj < 2; ++bj) { const f32x4 v0 = acc[ai][bj][m][0], v1 = acc[ai][bj][m][1];
;                     u32x4 w; w.x = pk_bf16(v0[0], v0[1]); w.y = pk_bf16(v0[2], v0[3]); w.z = pk_bf16(v1[0], v1[1]); w.w = pk_bf16(v1[2], v1[3]);
;                     *(u32x4*)(rowp + bj * HALF) = w; } }
	v_mov_b32_dpp v121, v97 row_ror:8 row_mask:0xf bank_mask:0xc
	v_mov_b32_dpp v94, v240 quad_perm:[0,1,2,3] row_mask:0xf bank_mask:0x3
	v_mov_b32_dpp v95, v241 quad_perm:[0,1,2,3] row_mask:0xf bank_mask:0x3
	v_mov_b32_dpp v96, v242 quad_perm:[0,1,2,3] row_mask:0xf bank_mask:0x3
	v_mov_b32_dpp v97, v243 quad_perm:[0,1,2,3] row_mask:0xf bank_mask:0x3
	global_store_dwordx4 v246, v[118:121], s[86:87]
	global_store_dwordx4 v247, v[94:97], s[86:87]
	v_cvt_pk_bf16_f32 v102, v102, v103
	v_cvt_pk_bf16_f32 v103, v104, v105
	v_cvt_pk_bf16_f32 v104, v98, v99
	v_cvt_pk_bf16_f32 v105, v100, v101
	v_cvt_pk_bf16_f32 v78, v78, v79
	v_cvt_pk_bf16_f32 v79, v80, v81
	v_cvt_pk_bf16_f32 v80, v74, v75
	v_cvt_pk_bf16_f32 v81, v76, v77
	v_mov_b32_dpp v240, v102 row_ror:8 row_mask:0xf bank_mask:0xf
	v_mov_b32_dpp v241, v103 row_ror:8 row_mask:0xf bank_mask:0xf
	v_mov_b32_dpp v242, v104 row_ror:8 row_mask:0xf bank_mask:0xf
	v_mov_b32_dpp v243, v105 row_ror:8 row_mask:0xf bank_mask:0xf
	v_mov_b32_dpp v102, v78 row_ror:8 row_mask:0xf bank_mask:0xc
	v_mov_b32_dpp v103, v79 row_ror:8 row_mask:0xf bank_mask:0xc
	v_mov_b32_dpp v104, v80 row_ror:8 row_mask:0xf bank_mask:0xc
	v_mov_b32_dpp v105, v81 row_ror:8 row_mask:0xf bank_mask:0xc
	v_mov_b32_dpp v78, v240 quad_perm:[0,1,2,3] row_mask:0xf bank_mask:0x3
	v_mov_b32_dpp v79, v241 quad_perm:[0,1,2,3] row_mask:0xf bank_mask:0x3
	v_mov_b32_dpp v80, v242 quad_perm:[0,1,2,3] row_mask:0xf bank_mask:0x3
	v_mov_b32_dpp v81, v243 quad_perm:[0,1,2,3] row_mask:0xf bank_mask:0x3
	global_store_dwordx4 v248, v[102:105], s[86:87]
	global_store_dwordx4 v249, v[78:81], s[86:87]
	v_cvt_pk_bf16_f32 v86, v86, v87
	v_cvt_pk_bf16_f32 v87, v88, v89
	v_cvt_pk_bf16_f32 v88, v82, v83
	v_cvt_pk_bf16_f32 v89, v84, v85
	v_cvt_pk_bf16_f32 v70, v70, v71
	v_cvt_pk_bf16_f32 v71, v72, v73
	v_cvt_pk_bf16_f32 v72, v66, v67
	v_cvt_pk_bf16_f32 v73, v68, v69
	v_mov_b32_dpp v240, v86 row_ror:8 row_mask:0xf bank_mask:0xf
	v_mov_b32_dpp v241, v87 row_ror:8 row_mask:0xf bank_mask:0xf
	v_mov_b32_dpp v242, v88 row_ror:8 row_mask:0xf bank_mask:0xf
	v_mov_b32_dpp v243, v89 row_ror:8 row_mask:0xf bank_mask:0xf
	v_mov_b32_dpp v86, v70 row_ror:8 row_mask:0xf bank_mask:0xc
	v_mov_b32_dpp v87, v71 row_ror:8 row_mask:0xf bank_mask:0xc
	v_mov_b32_dpp v88, v72 row_ror:8 row_mask:0xf bank_mask:0xc
	v_mov_b32_dpp v89, v73 row_ror:8 row_mask:0xf bank_mask:0xc
	v_mov_b32_dpp v70, v240 quad_perm:[0,1,2,3] row_mask:0xf bank_mask:0x3
	v_mov_b32_dpp v71, v241 quad_perm:[0,1,2,3] row_mask:0xf bank_mask:0x3
	v_mov_b32_dpp v72, v242 quad_perm:[0,1,2,3] row_mask:0xf bank_mask:0x3
	v_mov_b32_dpp v73, v243 quad_perm:[0,1,2,3] row_mask:0xf bank_mask:0x3
	global_store_dwordx4 v250, v[86:89], s[86:87]
	global_store_dwordx4 v251, v[70:73], s[86:87]
	v_cvt_pk_bf16_f32 v62, v62, v63
	v_cvt_pk_bf16_f32 v63, v64, v65
	v_cvt_pk_bf16_f32 v64, v58, v59
	v_cvt_pk_bf16_f32 v65, v60, v61
	v_cvt_pk_bf16_f32 v46, v46, v47
	v_cvt_pk_bf16_f32 v47, v48, v49
	v_cvt_pk_bf16_f32 v48, v42, v43
	v_cvt_pk_bf16_f32 v49, v44, v45
	v_mov_b32_dpp v240, v62 row_ror:8 row_mask:0xf bank_mask:0xf
	v_mov_b32_dpp v241, v63 row_ror:8 row_mask:0xf bank_mask:0xf
	v_mov_b32_dpp v242, v64 row_ror:8 row_mask:0xf bank_mask:0xf
	v_mov_b32_dpp v243, v65 row_ror:8 row_mask:0xf bank_mask:0xf
	v_mov_b32_dpp v62, v46 row_ror:8 row_mask:0xf bank_mask:0xc
	v_mov_b32_dpp v63, v47 row_ror:8 row_mask:0xf bank_mask:0xc
	v_mov_b32_dpp v64, v48 row_ror:8 row_mask:0xf bank_mask:0xc
	v_mov_b32_dpp v65, v49 row_ror:8 row_mask:0xf bank_mask:0xc
	v_mov_b32_dpp v46, v240 quad_perm:[0,1,2,3] row_mask:0xf bank_mask:0x3
	v_mov_b32_dpp v47, v241 quad_perm:[0,1,2,3] row_mask:0xf bank_mask:0x3
	v_mov_b32_dpp v48, v242 quad_perm:[0,1,2,3] row_mask:0xf bank_mask:0x3
; DI unsigned pk_bf16(float a, float b) { f32x2 v = {a, b}; bf2_t r = __builtin_convertvector(v, bf2_t); return __builtin_bit_cast(unsigned, r); }
;     DI void operator()(const f32x4 (&acc)[2][2][4][2], const Unit& u, int wr, int wc, int fr, int fq) const {
;     ...
;             for (int m = 0; m < 4; ++m) { bf16_t* rowp = O + (size_t)(row0 + ai * HALF + m * 16) * ldc + col0;
; #pragma unroll
;                 for (int bj = 0; bj < 2; ++bj) { const f32x4 v0 = acc[ai][bj][m][0], v1 = acc[ai][bj][m][1];
;                     u32x4 w; w.x = pk_bf16(v0[0], v0[1]); w.y = pk_bf16(v0[2], v0[3]); w.z = pk_bf16(v1[0], v1[1]); w.w = pk_bf16(v1[2], v1[3]);
;                     *(u32x4*)(rowp + bj * HALF) = w; } }
; template <class Epi, class Sched>
; DI void gemm_phase(LAS unsigned char* lds, const Gemm g, const Sched& S, const Epi& E) {
;     ...
;         E(acc, cur, wr, wc, fr, fq);
;         if (!has_next) break;
	v_mov_b32_dpp v49, v243 quad_perm:[0,1,2,3] row_mask:0xf bank_mask:0x3
	global_store_dwordx4 v252, v[62:65], s[86:87]
	global_store_dwordx4 v253, v[46:49], s[86:87]
	v_cvt_pk_bf16_f32 v54, v54, v55
	v_cvt_pk_bf16_f32 v55, v56, v57
	v_cvt_pk_bf16_f32 v56, v50, v51
	v_cvt_pk_bf16_f32 v57, v52, v53
	v_cvt_pk_bf16_f32 v30, v30, v31
	v_cvt_pk_bf16_f32 v31, v32, v33
	v_cvt_pk_bf16_f32 v32, v26, v27
	v_cvt_pk_bf16_f32 v33, v28, v29
	v_mov_b32_dpp v240, v54 row_ror:8 row_mask:0xf bank_mask:0xf
	v_mov_b32_dpp v241, v55 row_ror:8 row_mask:0xf bank_mask:0xf
	v_mov_b32_dpp v242, v56 row_ror:8 row_mask:0xf bank_mask:0xf
	v_mov_b32_dpp v243, v57 row_ror:8 row_mask:0xf bank_mask:0xf
	v_mov_b32_dpp v54, v30 row_ror:8 row_mask:0xf bank_mask:0xc
	v_mov_b32_dpp v55, v31 row_ror:8 row_mask:0xf bank_mask:0xc
	v_mov_b32_dpp v56, v32 row_ror:8 row_mask:0xf bank_mask:0xc
	v_mov_b32_dpp v57, v33 row_ror:8 row_mask:0xf bank_mask:0xc
	v_mov_b32_dpp v30, v240 quad_perm:[0,1,2,3] row_mask:0xf bank_mask:0x3
	v_mov_b32_dpp v31, v241 quad_perm:[0,1,2,3] row_mask:0xf bank_mask:0x3
	v_mov_b32_dpp v32, v242 quad_perm:[0,1,2,3] row_mask:0xf bank_mask:0x3
	v_mov_b32_dpp v33, v243 quad_perm:[0,1,2,3] row_mask:0xf bank_mask:0x3
	global_store_dwordx4 v254, v[54:57], s[86:87]
	global_store_dwordx4 v255, v[30:33], s[86:87]
	v_cvt_pk_bf16_f32 v38, v38, v39
	v_cvt_pk_bf16_f32 v39, v40, v41
	v_cvt_pk_bf16_f32 v40, v34, v35
	v_cvt_pk_bf16_f32 v41, v36, v37
	v_cvt_pk_bf16_f32 v14, v14, v15
	v_cvt_pk_bf16_f32 v15, v16, v17
	v_cvt_pk_bf16_f32 v16, v10, v11
	v_cvt_pk_bf16_f32 v17, v12, v13
	v_mov_b32_dpp v240, v38 row_ror:8 row_mask:0xf bank_mask:0xf
	v_mov_b32_dpp v241, v39 row_ror:8 row_mask:0xf bank_mask:0xf
	v_mov_b32_dpp v242, v40 row_ror:8 row_mask:0xf bank_mask:0xf
	v_mov_b32_dpp v243, v41 row_ror:8 row_mask:0xf bank_mask:0xf
	v_mov_b32_dpp v38, v14 row_ror:8 row_mask:0xf bank_mask:0xc
	v_mov_b32_dpp v39, v15 row_ror:8 row_mask:0xf bank_mask:0xc
	v_mov_b32_dpp v40, v16 row_ror:8 row_mask:0xf bank_mask:0xc
	v_mov_b32_dpp v41, v17 row_ror:8 row_mask:0xf bank_mask:0xc
	v_mov_b32_dpp v14, v240 quad_perm:[0,1,2,3] row_mask:0xf bank_mask:0x3
	v_mov_b32_dpp v15, v241 quad_perm:[0,1,2,3] row_mask:0xf bank_mask:0x3
	v_mov_b32_dpp v16, v242 quad_perm:[0,1,2,3] row_mask:0xf bank_mask:0x3
	v_mov_b32_dpp v17, v243 quad_perm:[0,1,2,3] row_mask:0xf bank_mask:0x3
	global_store_dwordx4 v158, v[38:41], s[86:87]
	global_store_dwordx4 v159, v[14:17], s[86:87]
	v_cvt_pk_bf16_f32 v22, v22, v23
	v_cvt_pk_bf16_f32 v23, v24, v25
	v_cvt_pk_bf16_f32 v24, v18, v19
	v_cvt_pk_bf16_f32 v25, v20, v21
	v_cvt_pk_bf16_f32 v6, v6, v7
	v_cvt_pk_bf16_f32 v7, v8, v9
	v_cvt_pk_bf16_f32 v8, v2, v3
	v_cvt_pk_bf16_f32 v9, v4, v5
	v_mov_b32_dpp v240, v22 row_ror:8 row_mask:0xf bank_mask:0xf
	v_mov_b32_dpp v241, v23 row_ror:8 row_mask:0xf bank_mask:0xf
	v_mov_b32_dpp v242, v24 row_ror:8 row_mask:0xf bank_mask:0xf
	v_mov_b32_dpp v243, v25 row_ror:8 row_mask:0xf bank_mask:0xf
	v_mov_b32_dpp v22, v6 row_ror:8 row_mask:0xf bank_mask:0xc
	v_mov_b32_dpp v23, v7 row_ror:8 row_mask:0xf bank_mask:0xc
	v_mov_b32_dpp v24, v8 row_ror:8 row_mask:0xf bank_mask:0xc
	v_mov_b32_dpp v25, v9 row_ror:8 row_mask:0xf bank_mask:0xc
	v_mov_b32_dpp v6, v240 quad_perm:[0,1,2,3] row_mask:0xf bank_mask:0x3
	v_mov_b32_dpp v7, v241 quad_perm:[0,1,2,3] row_mask:0xf bank_mask:0x3
	v_mov_b32_dpp v8, v242 quad_perm:[0,1,2,3] row_mask:0xf bank_mask:0x3
	v_mov_b32_dpp v9, v243 quad_perm:[0,1,2,3] row_mask:0xf bank_mask:0x3
	global_store_dwordx4 v160, v[22:25], s[86:87]
	global_store_dwordx4 v161, v[6:9], s[86:87]
	s_cbranch_vccz .LBB0_123
	s_waitcnt vmcnt(0)
	s_cmpk_gt_u32 s12, 0xff
	s_cbranch_scc1 .LBB0_134
	s_barrier

; DI int opaque_tid() { int t = threadIdx.x; asm volatile("" : "+v"(t)); return t; }
; #define PG8_STAGE(bufoff, gbase, voff) do { _Pragma("unroll") for (int _i = 0; _i < 2; ++_i) \
;         __builtin_amdgcn_global_load_lds((const unsigned*)((const char*)(gbase) + (voff)[_i]), (LAS unsigned*)(lds + (bufoff) + ldsw + _i * 8192), 16, 0, 0); } while (0)
; #define PG8_WAIT_V(n) asm volatile("s_waitcnt vmcnt(" #n ")" ::: "memory")
; #define PG8_BAR __builtin_amdgcn_s_barrier()
; template <class Epi, class Sched>
; DI void gemm_phase(LAS unsigned char* lds, const Gemm g, const Sched& S, const Epi& E) {
;     const int tid = opaque_tid(), wid = __builtin_amdgcn_readfirstlane(tid >> 6), lane = tid & 63, wr = wid >> 2, wc = wid & 3, fr = lane & 15, fq = lane >> 4;
;     const int K = g.ld, nt = g.K / BK;
;     unsigned voffA[2], voffB[2];
; #pragma unroll
;     for (int i = 0; i < 2; ++i) { int R, C; stage_rc(tid * 16 + i * 8192, R, C); const int Rb = Epi::PERM ? ((R & ~31) + perm32(R & 31)) : R;
;         voffA[i] = (unsigned)(R * K + C) * 2u; voffB[i] = (unsigned)(Rb * K + C) * 2u; }
;     const size_t kstep = (size_t)(BK * 2);
;     const size_t hstep = (size_t)HALF * K * 2;
;     const size_t tstep = 2 * hstep;
;     const unsigned ldsw = (unsigned)wid * 1024u;
;     const int aoff = lds_byte(wr * 64 + fr, fq * 8), boff = lds_byte(wc * 32 + fr, fq * 8);
;     ...
;     Unit cur, nxt; int ui = 0;
;     if (!S.next(0, cur)) return;
;     f32x4 acc[2][2][4][2];
; #pragma unroll
;     for (int a = 0; a < 2; ++a)
; #pragma unroll
;         for (int b = 0; b < 2; ++b)
; #pragma unroll
;             for (int m = 0; m < 4; ++m)
; #pragma unroll
;                 for (int n = 0; n < 2; ++n) acc[a][b][m][n] = (f32x4){0.f, 0.f, 0.f, 0.f};
;     bf16x8 At[4][2], B0[2][2], B1[2][2];
;     const char* cA = (const char*)g.A + (size_t)cur.pm * tstep + (size_t)cur.koff * 2; const char* cB = (const char*)g.Bt + (size_t)cur.pn * tstep + (size_t)cur.koff * 2;
;     PG8_STAGE(PG8_SB(0, 0), cB, voffB); PG8_STAGE(PG8_SA(0, 0), cA, voffA); PG8_STAGE(PG8_SB(0, 1), cB + hstep, voffB); PG8_STAGE(PG8_SA(0, 1), cA + hstep, voffA);
;     if (wr == 1) PG8_BAR;
;     PG8_WAIT_V(4); PG8_BAR;
;     PG8_STAGE(PG8_SB(1, 0), cB + kstep, voffB); PG8_STAGE(PG8_SA(1, 0), cA + kstep, voffA); PG8_STAGE(PG8_SB(1, 1), cB + hstep + kstep, voffB);
;     PG8_WAIT_V(6); PG8_BAR;
.LBB0_1182:
	s_cmp_lt_i32 s80, 8
	s_cselect_b64 s[0:1], -1, 0
	s_and_b64 s[4:5], s[0:1], s[4:5]
	s_andn2_b64 vcc, exec, s[4:5]
	s_cbranch_vccnz .LBB0_1195
	v_mov_b32_e32 v11, v1
	s_cmpk_gt_i32 s2, 0x65f
	s_nop 0
	v_readfirstlane_b32 s3, v11
	s_cbranch_scc1 .LBB0_1195
	v_lshlrev_b32_e32 v2, 4, v11
	v_add_u32_e32 v3, 0x2000, v2
	v_ashrrev_i32_e32 v4, 31, v3
	v_lshrrev_b32_e32 v4, 22, v4
	v_add_u32_e32 v4, v3, v4
	v_ashrrev_i32_e32 v10, 10, v4
	v_mul_i32_i24_e32 v4, 0x400, v10
	v_sub_u32_e32 v3, v3, v4
	v_lshrrev_b32_e32 v4, 4, v3
	v_bitop3_b32 v3, v4, v3, 32 bitop3:0x6c
	v_ashrrev_i32_e32 v4, 31, v3
	v_lshrrev_b32_e32 v4, 26, v4
	v_add_u32_e32 v4, v3, v4
	v_lshlrev_b32_e32 v5, 3, v10
	v_ashrrev_i32_e32 v12, 6, v4
	v_and_b32_e32 v5, -16, v5
	v_add_u32_e32 v5, v12, v5
	v_and_b32_e32 v6, 3, v12
	s_mov_b32 s4, 0x1fffe0
	v_lshrrev_b32_e32 v7, 2, v5
	v_lshlrev_b32_e32 v8, 1, v5
	v_and_b32_e32 v4, 0xc0, v4
	v_and_or_b32 v6, v5, s4, v6
	v_and_b32_e32 v7, 4, v7
	v_and_b32_e32 v8, 24, v8
	v_sub_u32_e32 v3, v3, v4
	v_mov_b32_e32 v4, 1
	v_or3_b32 v6, v6, v7, v8
	v_lshlrev_b32_e32 v7, 5, v10
	v_ashrrev_i16_sdwa v3, v4, sext(v3) dst_sel:DWORD dst_unused:UNUSED_PAD src0_sel:DWORD src1_sel:BYTE_0
	v_and_b32_e32 v7, 32, v7
	v_bfe_i32 v13, v3, 0, 16
	v_add_lshl_u32 v3, v7, v13, 1
	v_lshl_add_u32 v130, v6, 11, v3
	v_and_b32_e32 v240, 0x30000, v130
	v_add_u32_e32 v130, v130, v240
	v_lshl_add_u32 v132, v5, 11, v3
	v_bfe_i32 v3, v11, 27, 1
	v_lshrrev_b32_e32 v3, 22, v3
	v_add_u32_e32 v3, v2, v3
	v_and_b32_e32 v3, 0xfffffc00, v3
	v_sub_u32_e32 v2, v2, v3
	v_lshrrev_b32_e32 v3, 4, v2
	v_bitop3_b32 v3, v3, v2, 32 bitop3:0x6c
	v_ashrrev_i32_e32 v2, 31, v2
	v_lshrrev_b32_e32 v2, 26, v2
	v_add_u32_e32 v2, v3, v2
	v_ashrrev_i32_e32 v14, 6, v2
	v_ashrrev_i32_e32 v2, 31, v11
	v_lshrrev_b32_e32 v2, 26, v2
	v_add_u32_e32 v2, v11, v2
	v_ashrrev_i32_e32 v15, 6, v2
	s_ashr_i32 s6, s3, 6
	v_lshlrev_b32_e32 v2, 3, v15
	s_ashr_i32 s5, s3, 8
	s_lshl_b32 s12, s6, 10
	v_readlane_b32 s7, v238, 25
	v_and_b32_e32 v2, -16, v2
	s_cmp_lt_i32 s7, 0
	v_add_u32_e32 v2, v14, v2
	v_and_b32_e32 v5, 3, v14
	s_movk_i32 s13, 0xcd
	v_and_or_b32 v5, v2, s4, v5
	s_cselect_b32 s4, s13, 0xcc
	s_mul_i32 s4, s7, s4
	v_readlane_b32 s7, v238, 24
	v_lshrrev_b32_e32 v6, 2, v2
	v_lshlrev_b32_e32 v7, 1, v2
	s_add_i32 s4, s4, s7
	v_and_b32_e32 v6, 4, v6
	v_and_b32_e32 v7, 24, v7
	s_mul_hi_i32 s7, s4, 0x2aaaaaab
	v_or3_b32 v5, v5, v6, v7
	v_mul_i32_i24_e32 v7, 64, v14
	s_lshr_b32 s8, s7, 31
	s_ashr_i32 s7, s7, 5
	v_sub_u32_e32 v3, v3, v7
	s_add_i32 s7, s7, s8
	v_lshlrev_b32_e32 v6, 5, v15
	v_ashrrev_i16_sdwa v3, v4, sext(v3) dst_sel:DWORD dst_unused:UNUSED_PAD src0_sel:DWORD src1_sel:BYTE_0
	s_lshl_b32 s10, s7, 3
	v_and_b32_e32 v6, 32, v6
	v_bfe_i32 v16, v3, 0, 16
	s_sub_i32 s8, 0x44, s10
	v_add_lshl_u32 v3, v6, v16, 1
	s_min_u32 s11, s8, 8
	s_mulk_i32 s7, 0xc0
	v_lshl_add_u32 v134, v5, 11, v3
	v_and_b32_e32 v240, 0x30000, v134
	v_add_u32_e32 v134, v134, v240
	s_sub_i32 s7, s4, s7
	v_cvt_f32_ubyte0_e32 v5, s11
	v_cvt_f32_i32_e32 v4, s7
	v_rcp_iflag_f32_e32 v6, v5
	v_lshl_add_u32 v136, v2, 11, v3
	s_ashr_i32 s4, s7, 30
	s_or_b32 s4, s4, 1
	v_mul_f32_e32 v2, v4, v6
	v_trunc_f32_e32 v2, v2
	v_fma_f32 v3, -v2, v5, v4
	v_cvt_i32_f32_e32 v2, v2
	v_cmp_ge_f32_e64 s[8:9], |v3|, v5
	s_and_b64 s[8:9], s[8:9], exec
	s_cselect_b32 s4, s4, 0
	v_readfirstlane_b32 s8, v2
	s_add_i32 s4, s8, s4
	s_mul_i32 s8, s4, s11
	s_sub_i32 s7, s7, s8
	s_sext_i32_i16 s7, s7
	s_add_i32 s8, s10, s7
	s_ashr_i32 s9, s8, 31
	s_bfe_i64 s[16:17], s[4:5], 0x100000
	s_lshl_b64 s[10:11], s[8:9], 19
	s_lshl_b64 s[16:17], s[16:17], 19
	s_add_u32 s24, s88, s16
	s_addc_u32 s25, s89, s17
	s_add_i32 s9, s12, 0
	s_add_i32 m0, s9, 0x10000
	v_readlane_b32 s14, v238, 20
	global_load_lds_dwordx4 v134, s[24:25]
	s_add_i32 m0, s9, 0x12000
	v_readlane_b32 s15, v238, 21
	s_add_u32 s22, s14, s10
	global_load_lds_dwordx4 v130, s[24:25]
	s_addc_u32 s23, s15, s11
	s_mov_b32 m0, s9
	s_add_i32 s28, s9, 0x2000
	global_load_lds_dwordx4 v136, s[22:23]
	s_mov_b32 m0, s28
	s_add_u32 s10, s24, 0x10000
	global_load_lds_dwordx4 v132, s[22:23]
	s_addc_u32 s11, s25, 0
	s_add_i32 m0, s9, 0x14000
	v_mov_b32_e32 v135, 0
	global_load_lds_dwordx4 v134, s[10:11]
	s_add_i32 m0, s9, 0x16000
	v_mov_b32_e32 v131, v135
	global_load_lds_dwordx4 v130, s[10:11]
	s_add_u32 s10, s22, 0x40000
	s_addc_u32 s11, s23, 0
	s_add_i32 s29, s9, 0x4000
	s_mov_b32 m0, s29
	s_add_i32 s30, s9, 0x6000
	global_load_lds_dwordx4 v136, s[10:11]
	s_mov_b32 m0, s30
	v_mov_b32_e32 v137, v135
	global_load_lds_dwordx4 v132, s[10:11]
	v_mov_b32_e32 v133, v135
	s_mov_b32 s31, 0
	v_lshl_add_u64 v[8:9], s[24:25], 0, v[134:135]
	v_lshl_add_u64 v[6:7], s[24:25], 0, v[130:131]
	v_lshl_add_u64 v[4:5], s[22:23], 0, v[136:137]
	s_cmp_lg_u32 s5, 1
	v_lshl_add_u64 v[2:3], s[22:23], 0, v[132:133]
	s_cbranch_scc1 .LBB0_1186
	s_barrier
.LBB0_1186:
	s_lshl_b32 s6, s6, 5
	s_and_b32 s17, s6, 0x60
	s_mov_b64 s[6:7], 0x80
	s_add_i32 m0, s9, 0x18000
	v_lshl_add_u64 v[8:9], v[8:9], 0, s[6:7]
	s_lshl_b32 s16, s5, 13
	s_lshl_b32 s18, s17, 7
	s_waitcnt vmcnt(4)
	s_barrier
	global_load_lds_dwordx4 v[8:9], off
	v_lshl_add_u64 v[6:7], v[6:7], 0, s[6:7]
	s_add_i32 m0, s9, 0x1a000
	s_add_i32 s33, s9, 0x8000
	s_add_i32 s34, s9, 0xa000
	global_load_lds_dwordx4 v[6:7], off
	v_lshl_add_u64 v[4:5], v[4:5], 0, s[6:7]
	s_mov_b32 m0, s33
	s_add_u32 s10, s24, 0x10080
	global_load_lds_dwordx4 v[4:5], off
	v_lshl_add_u64 v[2:3], v[2:3], 0, s[6:7]
	s_mov_b32 m0, s34
	s_addc_u32 s11, s25, 0
	global_load_lds_dwordx4 v[2:3], off
	s_add_i32 m0, s9, 0x1c000
	v_lshl_add_u64 v[2:3], s[10:11], 0, v[134:135]
	global_load_lds_dwordx4 v[2:3], off
	v_lshl_add_u64 v[2:3], s[10:11], 0, v[130:131]
	s_add_i32 m0, s9, 0x1e000
	s_add_i32 s35, 0, 0x10000
	global_load_lds_dwordx4 v[2:3], off
	v_lshrrev_b32_e32 v3, 1, v11
	v_and_b32_e32 v3, 24, v3
	v_and_b32_e32 v2, 15, v11
	v_lshlrev_b32_e32 v4, 1, v3
	v_lshl_or_b32 v146, s5, 6, v2
	v_lshl_or_b32 v2, v2, 6, v4
	v_lshlrev_b32_e32 v4, 2, v11
	v_and_b32_e32 v4, 32, v4
	v_bitop3_b32 v5, v2, s16, v4 bitop3:0xde
	v_bitop3_b32 v147, v2, s18, v4 bitop3:0xde
	v_lshlrev_b32_e32 v2, 14, v15
	v_and_b32_e32 v2, 0xffff8000, v2
	v_lshl_or_b32 v148, s17, 1, v3
	v_lshl_add_u32 v2, v14, 11, v2
	v_and_b32_e32 v3, 1, v15
	v_lshl_or_b32 v2, v3, 6, v2
	v_lshl_add_u32 v138, v16, 1, v2
	v_lshlrev_b32_e32 v2, 14, v10
	v_and_b32_e32 v2, 0xffff8000, v2
	s_waitcnt vmcnt(6)
	v_lshl_add_u32 v2, v12, 11, v2
	v_and_b32_e32 v3, 1, v10
	v_lshl_or_b32 v2, v3, 6, v2
	s_add_i32 s36, 0, 0x14000
	s_sext_i32_i16 s38, s4
	v_mov_b32_e32 v139, v135
	v_lshl_add_u32 v140, v13, 1, v2
	v_mov_b32_e32 v141, v135
	v_mov_b64_e32 v[142:143], 0x660
	v_mov_b64_e32 v[144:145], 0x65f
	v_add_u32_e32 v149, s35, v147
	v_add_u32_e32 v150, 0, v5
	v_add_u32_e32 v151, s36, v147
	s_movk_i32 s37, 0x3000
	s_barrier
	s_waitcnt vmcnt(0)

; #define PG8_STAGE(bufoff, gbase, voff) do { _Pragma("unroll") for (int _i = 0; _i < 2; ++_i) \
;         __builtin_amdgcn_global_load_lds((const unsigned*)((const char*)(gbase) + (voff)[_i]), (LAS unsigned*)(lds + (bufoff) + ldsw + _i * 8192), 16, 0, 0); } while (0)
; #define PG8_LDA(dst, b, h) do { _Pragma("unroll") for (int m = 0; m < 4; ++m) _Pragma("unroll") for (int k = 0; k < 2; ++k) dst[m][k] = *(const LAS bf16x8*)(lds + PG8_SA(b, h) + aoff + m * 2048 + k * 1024); } while (0)
; #define PG8_LDB(dst, b, h) do { _Pragma("unroll") for (int n = 0; n < 2; ++n) _Pragma("unroll") for (int k = 0; k < 2; ++k) dst[n][k] = *(const LAS bf16x8*)(lds + PG8_SB(b, h) + boff + n * 2048 + k * 1024); } while (0)
; #define PG8_MMA(ai, bj, At, Bt) do { __builtin_amdgcn_s_setprio(1); _Pragma("unroll") for (int m = 0; m < 4; ++m) _Pragma("unroll") for (int n = 0; n < 2; ++n) _Pragma("unroll") for (int k = 0; k < 2; ++k) \
;         acc[ai][bj][m][n] = __builtin_amdgcn_mfma_f32_16x16x32_bf16(Bt[n][k], At[m][k], acc[ai][bj][m][n], 0, 0, 0); __builtin_amdgcn_s_setprio(0); } while (0)
; #define PG8_WAIT_V(n) asm volatile("s_waitcnt vmcnt(" #n ")" ::: "memory")
; #define PG8_WAIT_L(n) asm volatile("s_waitcnt lgkmcnt(" #n ")" ::: "memory")
; #define PG8_BAR __builtin_amdgcn_s_barrier()
; #define PG8_SCHED __builtin_amdgcn_sched_barrier(0)
; template <class Epi, class Sched>
; DI void gemm_phase(LAS unsigned char* lds, const Gemm g, const Sched& S, const Epi& E) {
;     ...
;             PG8_LDB(B0, 0, 0); PG8_SCHED; PG8_LDA(At, 0, 0); PG8_STAGE(PG8_SA(1, 1), a1 + hstep, voffA);
;             PG8_WAIT_L(8); PG8_BAR; PG8_WAIT_L(0); PG8_MMA(0, 0, At, B0); PG8_BAR; PG8_SCHED;
;             PG8_LDB(B1, 0, 1); PG8_STAGE(PG8_SB(0, 0), b2, voffB);
;             PG8_BAR; PG8_WAIT_L(0); PG8_MMA(0, 1, At, B1); PG8_BAR;
;             PG8_LDA(At, 0, 1); PG8_STAGE(PG8_SA(0, 0), a2, voffA);
;             PG8_BAR; PG8_WAIT_L(0); PG8_MMA(1, 0, At, B0); PG8_BAR; PG8_SCHED;
;             PG8_STAGE(PG8_SB(0, 1), b2 + hstep, voffB);
;             PG8_WAIT_V(6); PG8_BAR; PG8_MMA(1, 1, At, B1); PG8_BAR;
.LBB0_1190:
	ds_read_b128 v[152:155], v149
	ds_read_b128 v[156:159], v149 offset:1024
	ds_read_b128 v[168:171], v149 offset:2048
	ds_read_b128 v[172:175], v149 offset:3072
	s_add_u32 s24, s22, 0xfffc0080
	s_addc_u32 s25, s23, -1
	s_cmp_eq_u32 s43, 12
	s_cselect_b32 s27, s17, s25
	s_cselect_b32 s26, s39, s24
	s_cselect_b32 s25, s11, s42
	s_cselect_b32 s24, s40, s41
	v_lshl_add_u64 v[160:161], s[22:23], 0, v[138:139]
	s_add_i32 m0, s9, 0xc000
	ds_read_b128 v[176:179], v150
	ds_read_b128 v[180:183], v150 offset:1024
	ds_read_b128 v[184:187], v150 offset:2048
	ds_read_b128 v[188:191], v150 offset:3072
	ds_read_b128 v[192:195], v150 offset:4096
	ds_read_b128 v[198:201], v150 offset:5120
	ds_read_b128 v[202:205], v150 offset:6144
	ds_read_b128 v[206:209], v150 offset:7168
	global_load_lds_dwordx4 v[160:161], off
	v_lshl_add_u64 v[160:161], s[22:23], 0, v[140:141]
	s_add_i32 m0, s9, 0xe000
	s_nop 0
	global_load_lds_dwordx4 v[160:161], off
	s_waitcnt lgkmcnt(8)
	s_barrier
	s_waitcnt lgkmcnt(0)
	s_setprio 1
	s_waitcnt lgkmcnt(0)
	v_mfma_f32_16x16x32_bf16 v[126:129], v[152:155], v[176:179], v[126:129]
	v_mfma_f32_16x16x32_bf16 v[122:125], v[168:171], v[176:179], v[122:125]
	v_mfma_f32_16x16x32_bf16 v[118:121], v[152:155], v[184:187], v[118:121]
	v_mfma_f32_16x16x32_bf16 v[114:117], v[168:171], v[184:187], v[114:117]
	v_mfma_f32_16x16x32_bf16 v[102:105], v[152:155], v[192:195], v[102:105]
	v_mfma_f32_16x16x32_bf16 v[98:101], v[168:171], v[192:195], v[98:101]
	v_mfma_f32_16x16x32_bf16 v[86:89], v[152:155], v[202:205], v[86:89]
	v_mfma_f32_16x16x32_bf16 v[82:85], v[168:171], v[202:205], v[82:85]
	v_mfma_f32_16x16x32_bf16 v[126:129], v[156:159], v[180:183], v[126:129]
	v_mfma_f32_16x16x32_bf16 v[122:125], v[172:175], v[180:183], v[122:125]
	v_mfma_f32_16x16x32_bf16 v[118:121], v[156:159], v[188:191], v[118:121]
	v_mfma_f32_16x16x32_bf16 v[114:117], v[172:175], v[188:191], v[114:117]
	v_mfma_f32_16x16x32_bf16 v[102:105], v[156:159], v[198:201], v[102:105]
	v_mfma_f32_16x16x32_bf16 v[98:101], v[172:175], v[198:201], v[98:101]
	v_mfma_f32_16x16x32_bf16 v[86:89], v[156:159], v[206:209], v[86:89]
	v_mfma_f32_16x16x32_bf16 v[82:85], v[172:175], v[206:209], v[82:85]
	s_setprio 0
	s_barrier
	s_add_i32 s47, s35, s12
	v_lshl_add_u64 v[160:161], s[24:25], 0, v[134:135]
	s_mov_b32 m0, s47
	ds_read_b128 v[210:213], v151
	ds_read_b128 v[214:217], v151 offset:1024
	ds_read_b128 v[218:221], v151 offset:2048
	ds_read_b128 v[222:225], v151 offset:3072
	global_load_lds_dwordx4 v[160:161], off
	v_lshl_add_u64 v[226:227], s[24:25], 0, v[130:131]
	s_add_i32 m0, s47, 0x2000
	s_nop 0
	global_load_lds_dwordx4 v[226:227], off
	s_barrier
	s_waitcnt lgkmcnt(0)
	s_setprio 1
	s_waitcnt lgkmcnt(0)
	v_mfma_f32_16x16x32_bf16 v[110:113], v[210:213], v[176:179], v[110:113]
	v_mfma_f32_16x16x32_bf16 v[106:109], v[218:221], v[176:179], v[106:109]
	v_mfma_f32_16x16x32_bf16 v[94:97], v[210:213], v[184:187], v[94:97]
	v_mfma_f32_16x16x32_bf16 v[90:93], v[218:221], v[184:187], v[90:93]
	v_mfma_f32_16x16x32_bf16 v[78:81], v[210:213], v[192:195], v[78:81]
	v_mfma_f32_16x16x32_bf16 v[74:77], v[218:221], v[192:195], v[74:77]
	v_mfma_f32_16x16x32_bf16 v[70:73], v[210:213], v[202:205], v[70:73]
	v_mfma_f32_16x16x32_bf16 v[66:69], v[218:221], v[202:205], v[66:69]
	v_mfma_f32_16x16x32_bf16 v[110:113], v[214:217], v[180:183], v[110:113]
	v_mfma_f32_16x16x32_bf16 v[106:109], v[222:225], v[180:183], v[106:109]
	v_mfma_f32_16x16x32_bf16 v[94:97], v[214:217], v[188:191], v[94:97]
	v_mfma_f32_16x16x32_bf16 v[90:93], v[222:225], v[188:191], v[90:93]
	v_mfma_f32_16x16x32_bf16 v[78:81], v[214:217], v[198:201], v[78:81]
	v_mfma_f32_16x16x32_bf16 v[74:77], v[222:225], v[198:201], v[74:77]
	v_mfma_f32_16x16x32_bf16 v[70:73], v[214:217], v[206:209], v[70:73]
	v_mfma_f32_16x16x32_bf16 v[66:69], v[222:225], v[206:209], v[66:69]
	s_setprio 0
	s_mov_b32 m0, s9
	v_lshl_add_u64 v[228:229], s[26:27], 0, v[136:137]
	s_barrier
	ds_read_b128 v[176:179], v150 offset:16384
	ds_read_b128 v[180:183], v150 offset:17408
	ds_read_b128 v[184:187], v150 offset:18432
	ds_read_b128 v[188:191], v150 offset:19456
	ds_read_b128 v[192:195], v150 offset:20480
	ds_read_b128 v[198:201], v150 offset:21504
	ds_read_b128 v[202:205], v150 offset:22528
	ds_read_b128 v[206:209], v150 offset:23552
	global_load_lds_dwordx4 v[228:229], off
	v_lshl_add_u64 v[230:231], s[26:27], 0, v[132:133]
	s_mov_b32 m0, s28
	s_nop 0
	global_load_lds_dwordx4 v[230:231], off
	s_barrier
	s_waitcnt lgkmcnt(0)
	s_setprio 1
	s_waitcnt lgkmcnt(0)
	v_mfma_f32_16x16x32_bf16 v[62:65], v[152:155], v[176:179], v[62:65]
	v_mfma_f32_16x16x32_bf16 v[58:61], v[168:171], v[176:179], v[58:61]
	v_mfma_f32_16x16x32_bf16 v[54:57], v[152:155], v[184:187], v[54:57]
	v_mfma_f32_16x16x32_bf16 v[50:53], v[168:171], v[184:187], v[50:53]
	v_mfma_f32_16x16x32_bf16 v[38:41], v[152:155], v[192:195], v[38:41]
	v_mfma_f32_16x16x32_bf16 v[34:37], v[168:171], v[192:195], v[34:37]
	v_mfma_f32_16x16x32_bf16 v[22:25], v[152:155], v[202:205], v[22:25]
	v_mfma_f32_16x16x32_bf16 v[18:21], v[168:171], v[202:205], v[18:21]
	v_mfma_f32_16x16x32_bf16 v[62:65], v[156:159], v[180:183], v[62:65]
	v_mfma_f32_16x16x32_bf16 v[58:61], v[172:175], v[180:183], v[58:61]
	v_mfma_f32_16x16x32_bf16 v[54:57], v[156:159], v[188:191], v[54:57]
	v_mfma_f32_16x16x32_bf16 v[50:53], v[172:175], v[188:191], v[50:53]
	v_mfma_f32_16x16x32_bf16 v[38:41], v[156:159], v[198:201], v[38:41]
	v_mfma_f32_16x16x32_bf16 v[34:37], v[172:175], v[198:201], v[34:37]
	v_mfma_f32_16x16x32_bf16 v[22:25], v[156:159], v[206:209], v[22:25]
	v_mfma_f32_16x16x32_bf16 v[18:21], v[172:175], v[206:209], v[18:21]
	s_setprio 0
	s_barrier
; #define PG8_STAGE(bufoff, gbase, voff) do { _Pragma("unroll") for (int _i = 0; _i < 2; ++_i) \
;         __builtin_amdgcn_global_load_lds((const unsigned*)((const char*)(gbase) + (voff)[_i]), (LAS unsigned*)(lds + (bufoff) + ldsw + _i * 8192), 16, 0, 0); } while (0)
; #define PG8_LDA(dst, b, h) do { _Pragma("unroll") for (int m = 0; m < 4; ++m) _Pragma("unroll") for (int k = 0; k < 2; ++k) dst[m][k] = *(const LAS bf16x8*)(lds + PG8_SA(b, h) + aoff + m * 2048 + k * 1024); } while (0)
; #define PG8_LDB(dst, b, h) do { _Pragma("unroll") for (int n = 0; n < 2; ++n) _Pragma("unroll") for (int k = 0; k < 2; ++k) dst[n][k] = *(const LAS bf16x8*)(lds + PG8_SB(b, h) + boff + n * 2048 + k * 1024); } while (0)
; #define PG8_MMA(ai, bj, At, Bt) do { __builtin_amdgcn_s_setprio(1); _Pragma("unroll") for (int m = 0; m < 4; ++m) _Pragma("unroll") for (int n = 0; n < 2; ++n) _Pragma("unroll") for (int k = 0; k < 2; ++k) \
;         acc[ai][bj][m][n] = __builtin_amdgcn_mfma_f32_16x16x32_bf16(Bt[n][k], At[m][k], acc[ai][bj][m][n], 0, 0, 0); __builtin_amdgcn_s_setprio(0); } while (0)
; #define PG8_WAIT_V(n) asm volatile("s_waitcnt vmcnt(" #n ")" ::: "memory")
; #define PG8_WAIT_L(n) asm volatile("s_waitcnt lgkmcnt(" #n ")" ::: "memory")
; #define PG8_BAR __builtin_amdgcn_s_barrier()
; #define PG8_SCHED __builtin_amdgcn_sched_barrier(0)
; template <class Epi, class Sched>
; DI void gemm_phase(LAS unsigned char* lds, const Gemm g, const Sched& S, const Epi& E) {
;     ...
;             PG8_STAGE(PG8_SB(0, 1), b2 + hstep, voffB);
;             PG8_WAIT_V(6); PG8_BAR; PG8_MMA(1, 1, At, B1); PG8_BAR;
;             PG8_LDB(B0, 1, 0); PG8_SCHED; PG8_LDA(At, 1, 0); PG8_STAGE(PG8_SA(0, 1), a2 + hstep, voffA);
;             PG8_WAIT_L(8); PG8_BAR; PG8_WAIT_L(0); PG8_MMA(0, 0, At, B0); PG8_BAR; PG8_SCHED;
;             PG8_LDB(B1, 1, 1); PG8_STAGE(PG8_SB(1, 0), b3, voffB);
;             PG8_BAR; PG8_WAIT_L(0); PG8_MMA(0, 1, At, B1); PG8_BAR;
;             PG8_LDA(At, 1, 1); PG8_STAGE(PG8_SA(1, 0), a3, voffA);
;             PG8_BAR; PG8_WAIT_L(0); PG8_MMA(1, 0, At, B0); PG8_BAR; PG8_SCHED;
	s_add_u32 s54, s24, 0x10000
	s_addc_u32 s55, s25, 0
	s_add_i32 s47, s36, s12
	v_lshl_add_u64 v[152:153], s[54:55], 0, v[134:135]
	s_mov_b32 m0, s47
	s_nop 0
	global_load_lds_dwordx4 v[152:153], off
	v_lshl_add_u64 v[152:153], s[54:55], 0, v[130:131]
	s_add_i32 m0, s47, 0x2000
	s_nop 0
	global_load_lds_dwordx4 v[152:153], off
	s_waitcnt vmcnt(6)
	s_barrier
	s_setprio 1
	v_mfma_f32_16x16x32_bf16 v[46:49], v[210:213], v[176:179], v[46:49]
	v_mfma_f32_16x16x32_bf16 v[42:45], v[218:221], v[176:179], v[42:45]
	v_mfma_f32_16x16x32_bf16 v[30:33], v[210:213], v[184:187], v[30:33]
	v_mfma_f32_16x16x32_bf16 v[26:29], v[218:221], v[184:187], v[26:29]
	v_mfma_f32_16x16x32_bf16 v[14:17], v[210:213], v[192:195], v[14:17]
	v_mfma_f32_16x16x32_bf16 v[10:13], v[218:221], v[192:195], v[10:13]
	v_mfma_f32_16x16x32_bf16 v[6:9], v[210:213], v[202:205], v[6:9]
	v_mfma_f32_16x16x32_bf16 v[2:5], v[218:221], v[202:205], v[2:5]
	v_mfma_f32_16x16x32_bf16 v[46:49], v[214:217], v[180:183], v[46:49]
	v_mfma_f32_16x16x32_bf16 v[42:45], v[222:225], v[180:183], v[42:45]
	v_mfma_f32_16x16x32_bf16 v[30:33], v[214:217], v[188:191], v[30:33]
	v_mfma_f32_16x16x32_bf16 v[26:29], v[222:225], v[188:191], v[26:29]
	v_mfma_f32_16x16x32_bf16 v[14:17], v[214:217], v[198:201], v[14:17]
	v_mfma_f32_16x16x32_bf16 v[10:13], v[222:225], v[198:201], v[10:13]
	v_mfma_f32_16x16x32_bf16 v[6:9], v[214:217], v[206:209], v[6:9]
	v_mfma_f32_16x16x32_bf16 v[2:5], v[222:225], v[206:209], v[2:5]
	s_setprio 0
	s_add_i32 s47, 0, 0x18000
	v_add_u32_e32 v165, s47, v147
	s_barrier
	ds_read_b128 v[152:155], v165
	ds_read_b128 v[156:159], v165 offset:1024
	ds_read_b128 v[168:171], v165 offset:2048
	ds_read_b128 v[172:175], v165 offset:3072
	s_add_u32 s26, s26, 0x40000
	s_addc_u32 s27, s27, 0
	s_mov_b32 m0, s29
	v_lshl_add_u64 v[210:211], s[26:27], 0, v[136:137]
	ds_read_b128 v[176:179], v150 offset:32768
	ds_read_b128 v[180:183], v150 offset:33792
	ds_read_b128 v[184:187], v150 offset:34816
	ds_read_b128 v[188:191], v150 offset:35840
	ds_read_b128 v[192:195], v150 offset:36864
	ds_read_b128 v[198:201], v150 offset:37888
	ds_read_b128 v[202:205], v150 offset:38912
	ds_read_b128 v[206:209], v150 offset:39936
	global_load_lds_dwordx4 v[210:211], off
	v_lshl_add_u64 v[210:211], s[26:27], 0, v[132:133]
	s_mov_b32 m0, s30
	s_nop 0
	global_load_lds_dwordx4 v[210:211], off
	s_waitcnt lgkmcnt(8)
	s_barrier
	s_waitcnt lgkmcnt(0)
	s_setprio 1
	s_waitcnt lgkmcnt(0)
	v_mfma_f32_16x16x32_bf16 v[126:129], v[152:155], v[176:179], v[126:129]
	v_mfma_f32_16x16x32_bf16 v[122:125], v[168:171], v[176:179], v[122:125]
	v_mfma_f32_16x16x32_bf16 v[118:121], v[152:155], v[184:187], v[118:121]
	v_mfma_f32_16x16x32_bf16 v[114:117], v[168:171], v[184:187], v[114:117]
	v_mfma_f32_16x16x32_bf16 v[102:105], v[152:155], v[192:195], v[102:105]
	v_mfma_f32_16x16x32_bf16 v[98:101], v[168:171], v[192:195], v[98:101]
	v_mfma_f32_16x16x32_bf16 v[86:89], v[152:155], v[202:205], v[86:89]
	v_mfma_f32_16x16x32_bf16 v[82:85], v[168:171], v[202:205], v[82:85]
	v_mfma_f32_16x16x32_bf16 v[126:129], v[156:159], v[180:183], v[126:129]
	v_mfma_f32_16x16x32_bf16 v[122:125], v[172:175], v[180:183], v[122:125]
	v_mfma_f32_16x16x32_bf16 v[118:121], v[156:159], v[188:191], v[118:121]
	v_mfma_f32_16x16x32_bf16 v[114:117], v[172:175], v[188:191], v[114:117]
	v_mfma_f32_16x16x32_bf16 v[102:105], v[156:159], v[198:201], v[102:105]
	v_mfma_f32_16x16x32_bf16 v[98:101], v[172:175], v[198:201], v[98:101]
	v_mfma_f32_16x16x32_bf16 v[86:89], v[156:159], v[206:209], v[86:89]
	v_mfma_f32_16x16x32_bf16 v[82:85], v[172:175], v[206:209], v[82:85]
	s_setprio 0
	s_barrier
	s_add_i32 s26, 0, 0x1c000
	s_add_i32 s27, s47, s12
	v_add_u32_e32 v165, s26, v147
	v_lshl_add_u64 v[160:161], v[160:161], 0, s[6:7]
	s_mov_b32 m0, s27
	ds_read_b128 v[210:213], v165
	ds_read_b128 v[214:217], v165 offset:1024
	ds_read_b128 v[218:221], v165 offset:2048
	ds_read_b128 v[222:225], v165 offset:3072
	global_load_lds_dwordx4 v[160:161], off
	v_lshl_add_u64 v[160:161], v[226:227], 0, s[6:7]
	s_add_i32 m0, s27, 0x2000
	s_nop 0
	global_load_lds_dwordx4 v[160:161], off
	s_barrier
	s_waitcnt lgkmcnt(0)
	s_setprio 1
	s_waitcnt lgkmcnt(0)
	v_mfma_f32_16x16x32_bf16 v[110:113], v[210:213], v[176:179], v[110:113]
	v_mfma_f32_16x16x32_bf16 v[106:109], v[218:221], v[176:179], v[106:109]
	v_mfma_f32_16x16x32_bf16 v[94:97], v[210:213], v[184:187], v[94:97]
	v_mfma_f32_16x16x32_bf16 v[90:93], v[218:221], v[184:187], v[90:93]
	v_mfma_f32_16x16x32_bf16 v[78:81], v[210:213], v[192:195], v[78:81]
	v_mfma_f32_16x16x32_bf16 v[74:77], v[218:221], v[192:195], v[74:77]
	v_mfma_f32_16x16x32_bf16 v[70:73], v[210:213], v[202:205], v[70:73]
	v_mfma_f32_16x16x32_bf16 v[66:69], v[218:221], v[202:205], v[66:69]
	v_mfma_f32_16x16x32_bf16 v[110:113], v[214:217], v[180:183], v[110:113]
	v_mfma_f32_16x16x32_bf16 v[106:109], v[222:225], v[180:183], v[106:109]
	v_mfma_f32_16x16x32_bf16 v[94:97], v[214:217], v[188:191], v[94:97]
	v_mfma_f32_16x16x32_bf16 v[90:93], v[222:225], v[188:191], v[90:93]
	v_mfma_f32_16x16x32_bf16 v[78:81], v[214:217], v[198:201], v[78:81]
	v_mfma_f32_16x16x32_bf16 v[74:77], v[222:225], v[198:201], v[74:77]
	v_mfma_f32_16x16x32_bf16 v[70:73], v[214:217], v[206:209], v[70:73]
	v_mfma_f32_16x16x32_bf16 v[66:69], v[222:225], v[206:209], v[66:69]
	s_setprio 0
	s_mov_b32 m0, s33
	v_lshl_add_u64 v[160:161], v[228:229], 0, s[6:7]
	s_barrier
	ds_read_b128 v[176:179], v150 offset:49152
	ds_read_b128 v[180:183], v150 offset:50176
	ds_read_b128 v[184:187], v150 offset:51200
	ds_read_b128 v[188:191], v150 offset:52224
	ds_read_b128 v[192:195], v150 offset:53248
	ds_read_b128 v[198:201], v150 offset:54272
	ds_read_b128 v[202:205], v150 offset:55296
	ds_read_b128 v[206:209], v150 offset:56320
	global_load_lds_dwordx4 v[160:161], off
	v_lshl_add_u64 v[160:161], v[230:231], 0, s[6:7]
	s_mov_b32 m0, s34
	s_nop 0
	global_load_lds_dwordx4 v[160:161], off
	s_barrier
; DI unsigned pk_bf16(float a, float b) { f32x2 v = {a, b}; bf2_t r = __builtin_convertvector(v, bf2_t); return __builtin_bit_cast(unsigned, r); }
; #define PG8_STAGE(bufoff, gbase, voff) do { _Pragma("unroll") for (int _i = 0; _i < 2; ++_i) \
;         __builtin_amdgcn_global_load_lds((const unsigned*)((const char*)(gbase) + (voff)[_i]), (LAS unsigned*)(lds + (bufoff) + ldsw + _i * 8192), 16, 0, 0); } while (0)
; #define PG8_MMA(ai, bj, At, Bt) do { __builtin_amdgcn_s_setprio(1); _Pragma("unroll") for (int m = 0; m < 4; ++m) _Pragma("unroll") for (int n = 0; n < 2; ++n) _Pragma("unroll") for (int k = 0; k < 2; ++k) \
;         acc[ai][bj][m][n] = __builtin_amdgcn_mfma_f32_16x16x32_bf16(Bt[n][k], At[m][k], acc[ai][bj][m][n], 0, 0, 0); __builtin_amdgcn_s_setprio(0); } while (0)
; #define PG8_WAIT_V(n) asm volatile("s_waitcnt vmcnt(" #n ")" ::: "memory")
; #define PG8_WAIT_L(n) asm volatile("s_waitcnt lgkmcnt(" #n ")" ::: "memory")
; #define PG8_BAR __builtin_amdgcn_s_barrier()
; #define PG8_SCHED __builtin_amdgcn_sched_barrier(0)
;     DI void operator()(const f32x4 (&acc)[2][2][4][2], const Unit& u, int wr, int wc, int fr, int fq) const {
;     ...
;             for (int m = 0; m < 4; ++m) { bf16_t* rowp = O + (size_t)(row0 + ai * HALF + m * 16) * ldc + col0;
; #pragma unroll
;                 for (int bj = 0; bj < 2; ++bj) { const f32x4 v0 = acc[ai][bj][m][0], v1 = acc[ai][bj][m][1];
;                     u32x4 w; w.x = pk_bf16(v0[0], v0[1]); w.y = pk_bf16(v0[2], v0[3]); w.z = pk_bf16(v1[0], v1[1]); w.w = pk_bf16(v1[2], v1[3]);
;                     *(u32x4*)(rowp + bj * HALF) = w; } }
; template <class Epi, class Sched>
; DI void gemm_phase(LAS unsigned char* lds, const Gemm g, const Sched& S, const Epi& E) {
;     ...
;             PG8_BAR; PG8_WAIT_L(0); PG8_MMA(1, 0, At, B0); PG8_BAR; PG8_SCHED;
;             PG8_STAGE(PG8_SB(1, 1), b3 + hstep, voffB);
;             PG8_WAIT_V(6); PG8_BAR; PG8_MMA(1, 1, At, B1); PG8_BAR;
	s_waitcnt lgkmcnt(0)
	s_setprio 1
	s_waitcnt lgkmcnt(0)
	v_mfma_f32_16x16x32_bf16 v[62:65], v[152:155], v[176:179], v[62:65]
	v_mfma_f32_16x16x32_bf16 v[58:61], v[168:171], v[176:179], v[58:61]
	v_mfma_f32_16x16x32_bf16 v[54:57], v[152:155], v[184:187], v[54:57]
	v_mfma_f32_16x16x32_bf16 v[50:53], v[168:171], v[184:187], v[50:53]
	v_mfma_f32_16x16x32_bf16 v[38:41], v[152:155], v[192:195], v[38:41]
	v_mfma_f32_16x16x32_bf16 v[34:37], v[168:171], v[192:195], v[34:37]
	v_mfma_f32_16x16x32_bf16 v[22:25], v[152:155], v[202:205], v[22:25]
	v_mfma_f32_16x16x32_bf16 v[18:21], v[168:171], v[202:205], v[18:21]
	v_mfma_f32_16x16x32_bf16 v[62:65], v[156:159], v[180:183], v[62:65]
	v_mfma_f32_16x16x32_bf16 v[58:61], v[172:175], v[180:183], v[58:61]
	v_mfma_f32_16x16x32_bf16 v[54:57], v[156:159], v[188:191], v[54:57]
	v_mfma_f32_16x16x32_bf16 v[50:53], v[172:175], v[188:191], v[50:53]
	v_mfma_f32_16x16x32_bf16 v[38:41], v[156:159], v[198:201], v[38:41]
	v_mfma_f32_16x16x32_bf16 v[34:37], v[172:175], v[198:201], v[34:37]
	v_mfma_f32_16x16x32_bf16 v[22:25], v[156:159], v[206:209], v[22:25]
	v_mfma_f32_16x16x32_bf16 v[18:21], v[172:175], v[206:209], v[18:21]
	s_setprio 0
	s_barrier
	s_add_u32 s24, s24, 0x10080
	s_addc_u32 s25, s25, 0
	s_add_i32 s26, s26, s12
	v_lshl_add_u64 v[152:153], s[24:25], 0, v[134:135]
	s_mov_b32 m0, s26
	s_nop 0
	global_load_lds_dwordx4 v[152:153], off
	v_lshl_add_u64 v[152:153], s[24:25], 0, v[130:131]
	s_add_i32 m0, s26, 0x2000
	s_nop 0
	global_load_lds_dwordx4 v[152:153], off
	s_waitcnt vmcnt(6)
	s_barrier
	s_setprio 1
	v_mfma_f32_16x16x32_bf16 v[46:49], v[210:213], v[176:179], v[46:49]
	v_mfma_f32_16x16x32_bf16 v[42:45], v[218:221], v[176:179], v[42:45]
	v_mfma_f32_16x16x32_bf16 v[30:33], v[210:213], v[184:187], v[30:33]
	v_mfma_f32_16x16x32_bf16 v[26:29], v[218:221], v[184:187], v[26:29]
	v_mfma_f32_16x16x32_bf16 v[14:17], v[210:213], v[192:195], v[14:17]
	v_mfma_f32_16x16x32_bf16 v[10:13], v[218:221], v[192:195], v[10:13]
	v_mfma_f32_16x16x32_bf16 v[6:9], v[210:213], v[202:205], v[6:9]
	v_mfma_f32_16x16x32_bf16 v[2:5], v[218:221], v[202:205], v[2:5]
	v_mfma_f32_16x16x32_bf16 v[46:49], v[214:217], v[180:183], v[46:49]
	v_mfma_f32_16x16x32_bf16 v[42:45], v[222:225], v[180:183], v[42:45]
	v_mfma_f32_16x16x32_bf16 v[30:33], v[214:217], v[188:191], v[30:33]
	v_mfma_f32_16x16x32_bf16 v[26:29], v[222:225], v[188:191], v[26:29]
	v_mfma_f32_16x16x32_bf16 v[14:17], v[214:217], v[198:201], v[14:17]
	v_mfma_f32_16x16x32_bf16 v[10:13], v[222:225], v[198:201], v[10:13]
	v_mfma_f32_16x16x32_bf16 v[6:9], v[214:217], v[206:209], v[6:9]
	v_mfma_f32_16x16x32_bf16 v[2:5], v[222:225], v[206:209], v[2:5]
	s_setprio 0
	s_add_i32 s43, s43, 2
	s_add_u32 s22, s22, 0x100
	s_addc_u32 s23, s23, 0
	s_add_u32 s41, s41, 0x100
	s_addc_u32 s42, s42, 0
	s_cmp_gt_u32 s43, 13
	s_barrier
	s_cbranch_scc0 .LBB0_1190
	v_and_b32_e32 v152, 8, v146
	v_sub_u32_e32 v153, v146, v152
	v_lshl_add_u32 v153, s8, 8, v153
	v_lshl_add_u32 v152, v152, 2, v148
	v_lshl_or_b32 v152, s38, 8, v152
	v_mul_u32_u24_e32 v153, 0x3000, v153
	v_lshl_add_u32 v244, v152, 1, v153
	v_add_u32_e32 v245, 0x18000, v244
	v_add_u32_e32 v246, 0x30000, v244
	v_add_u32_e32 v247, 0x48000, v244
	v_add_u32_e32 v248, 0x60000, v244
	v_add_u32_e32 v249, 0x78000, v244
	v_add_u32_e32 v250, 0x90000, v244
	v_add_u32_e32 v251, 0xa8000, v244
	v_add_u32_e32 v252, 0x180000, v244
	v_add_u32_e32 v253, 0x198000, v244
	v_add_u32_e32 v254, 0x1b0000, v244
	v_add_u32_e32 v255, 0x1c8000, v244
	v_add_u32_e32 v154, 0x1e0000, v244
	v_add_u32_e32 v155, 0x1f8000, v244
	v_add_u32_e32 v156, 0x210000, v244
	v_add_u32_e32 v157, 0x228000, v244
	s_and_b64 vcc, exec, s[4:5]
	s_mov_b32 s38, s10
	s_mov_b32 s8, s16
	s_mov_b64 s[24:25], s[20:21]
	s_mov_b64 s[22:23], s[18:19]
	v_cvt_pk_bf16_f32 v126, v126, v127
	v_cvt_pk_bf16_f32 v127, v128, v129
	v_cvt_pk_bf16_f32 v128, v122, v123
	v_cvt_pk_bf16_f32 v129, v124, v125
	v_cvt_pk_bf16_f32 v110, v110, v111
	v_cvt_pk_bf16_f32 v111, v112, v113
	v_cvt_pk_bf16_f32 v112, v106, v107
	v_cvt_pk_bf16_f32 v113, v108, v109
	v_mov_b32_dpp v240, v126 row_ror:8 row_mask:0xf bank_mask:0xf
	v_mov_b32_dpp v241, v127 row_ror:8 row_mask:0xf bank_mask:0xf
	v_mov_b32_dpp v242, v128 row_ror:8 row_mask:0xf bank_mask:0xf
	v_mov_b32_dpp v243, v129 row_ror:8 row_mask:0xf bank_mask:0xf
	v_mov_b32_dpp v126, v110 row_ror:8 row_mask:0xf bank_mask:0xc
	v_mov_b32_dpp v127, v111 row_ror:8 row_mask:0xf bank_mask:0xc
	v_mov_b32_dpp v128, v112 row_ror:8 row_mask:0xf bank_mask:0xc
	v_mov_b32_dpp v129, v113 row_ror:8 row_mask:0xf bank_mask:0xc
	v_mov_b32_dpp v110, v240 quad_perm:[0,1,2,3] row_mask:0xf bank_mask:0x3
	v_mov_b32_dpp v111, v241 quad_perm:[0,1,2,3] row_mask:0xf bank_mask:0x3
	v_mov_b32_dpp v112, v242 quad_perm:[0,1,2,3] row_mask:0xf bank_mask:0x3
	v_mov_b32_dpp v113, v243 quad_perm:[0,1,2,3] row_mask:0xf bank_mask:0x3
	global_store_dwordx4 v244, v[126:129], s[86:87]
	global_store_dwordx4 v245, v[110:113], s[86:87]
	v_cvt_pk_bf16_f32 v118, v118, v119
	v_cvt_pk_bf16_f32 v119, v120, v121
	v_cvt_pk_bf16_f32 v120, v114, v115
	v_cvt_pk_bf16_f32 v121, v116, v117
	v_cvt_pk_bf16_f32 v94, v94, v95
	v_cvt_pk_bf16_f32 v95, v96, v97
	v_cvt_pk_bf16_f32 v96, v90, v91
	v_cvt_pk_bf16_f32 v97, v92, v93
	v_mov_b32_dpp v240, v118 row_ror:8 row_mask:0xf bank_mask:0xf
	v_mov_b32_dpp v241, v119 row_ror:8 row_mask:0xf bank_mask:0xf
	v_mov_b32_dpp v242, v120 row_ror:8 row_mask:0xf bank_mask:0xf
	v_mov_b32_dpp v243, v121 row_ror:8 row_mask:0xf bank_mask:0xf
	v_mov_b32_dpp v118, v94 row_ror:8 row_mask:0xf bank_mask:0xc
	v_mov_b32_dpp v119, v95 row_ror:8 row_mask:0xf bank_mask:0xc
	v_mov_b32_dpp v120, v96 row_ror:8 row_mask:0xf bank_mask:0xc
; DI unsigned pk_bf16(float a, float b) { f32x2 v = {a, b}; bf2_t r = __builtin_convertvector(v, bf2_t); return __builtin_bit_cast(unsigned, r); }
;     DI void operator()(const f32x4 (&acc)[2][2][4][2], const Unit& u, int wr, int wc, int fr, int fq) const {
;     ...
;             for (int m = 0; m < 4; ++m) { bf16_t* rowp = O + (size_t)(row0 + ai * HALF + m * 16) * ldc + col0;
; #pragma unroll
;                 for (int bj = 0; bj < 2; ++bj) { const f32x4 v0 = acc[ai][bj][m][0], v1 = acc[ai][bj][m][1];
;                     u32x4 w; w.x = pk_bf16(v0[0], v0[1]); w.y = pk_bf16(v0[2], v0[3]); w.z = pk_bf16(v1[0], v1[1]); w.w = pk_bf16(v1[2], v1[3]);
;                     *(u32x4*)(rowp + bj * HALF) = w; } }
	v_mov_b32_dpp v121, v97 row_ror:8 row_mask:0xf bank_mask:0xc
	v_mov_b32_dpp v94, v240 quad_perm:[0,1,2,3] row_mask:0xf bank_mask:0x3
	v_mov_b32_dpp v95, v241 quad_perm:[0,1,2,3] row_mask:0xf bank_mask:0x3
	v_mov_b32_dpp v96, v242 quad_perm:[0,1,2,3] row_mask:0xf bank_mask:0x3
	v_mov_b32_dpp v97, v243 quad_perm:[0,1,2,3] row_mask:0xf bank_mask:0x3
	global_store_dwordx4 v246, v[118:121], s[86:87]
	global_store_dwordx4 v247, v[94:97], s[86:87]
	v_cvt_pk_bf16_f32 v102, v102, v103
	v_cvt_pk_bf16_f32 v103, v104, v105
	v_cvt_pk_bf16_f32 v104, v98, v99
	v_cvt_pk_bf16_f32 v105, v100, v101
	v_cvt_pk_bf16_f32 v78, v78, v79
	v_cvt_pk_bf16_f32 v79, v80, v81
	v_cvt_pk_bf16_f32 v80, v74, v75
	v_cvt_pk_bf16_f32 v81, v76, v77
	v_mov_b32_dpp v240, v102 row_ror:8 row_mask:0xf bank_mask:0xf
	v_mov_b32_dpp v241, v103 row_ror:8 row_mask:0xf bank_mask:0xf
	v_mov_b32_dpp v242, v104 row_ror:8 row_mask:0xf bank_mask:0xf
	v_mov_b32_dpp v243, v105 row_ror:8 row_mask:0xf bank_mask:0xf
	v_mov_b32_dpp v102, v78 row_ror:8 row_mask:0xf bank_mask:0xc
	v_mov_b32_dpp v103, v79 row_ror:8 row_mask:0xf bank_mask:0xc
	v_mov_b32_dpp v104, v80 row_ror:8 row_mask:0xf bank_mask:0xc
	v_mov_b32_dpp v105, v81 row_ror:8 row_mask:0xf bank_mask:0xc
	v_mov_b32_dpp v78, v240 quad_perm:[0,1,2,3] row_mask:0xf bank_mask:0x3
	v_mov_b32_dpp v79, v241 quad_perm:[0,1,2,3] row_mask:0xf bank_mask:0x3
	v_mov_b32_dpp v80, v242 quad_perm:[0,1,2,3] row_mask:0xf bank_mask:0x3
	v_mov_b32_dpp v81, v243 quad_perm:[0,1,2,3] row_mask:0xf bank_mask:0x3
	global_store_dwordx4 v248, v[102:105], s[86:87]
	global_store_dwordx4 v249, v[78:81], s[86:87]
	v_cvt_pk_bf16_f32 v86, v86, v87
	v_cvt_pk_bf16_f32 v87, v88, v89
	v_cvt_pk_bf16_f32 v88, v82, v83
	v_cvt_pk_bf16_f32 v89, v84, v85
	v_cvt_pk_bf16_f32 v70, v70, v71
	v_cvt_pk_bf16_f32 v71, v72, v73
	v_cvt_pk_bf16_f32 v72, v66, v67
	v_cvt_pk_bf16_f32 v73, v68, v69
	v_mov_b32_dpp v240, v86 row_ror:8 row_mask:0xf bank_mask:0xf
	v_mov_b32_dpp v241, v87 row_ror:8 row_mask:0xf bank_mask:0xf
	v_mov_b32_dpp v242, v88 row_ror:8 row_mask:0xf bank_mask:0xf
	v_mov_b32_dpp v243, v89 row_ror:8 row_mask:0xf bank_mask:0xf
	v_mov_b32_dpp v86, v70 row_ror:8 row_mask:0xf bank_mask:0xc
	v_mov_b32_dpp v87, v71 row_ror:8 row_mask:0xf bank_mask:0xc
	v_mov_b32_dpp v88, v72 row_ror:8 row_mask:0xf bank_mask:0xc
	v_mov_b32_dpp v89, v73 row_ror:8 row_mask:0xf bank_mask:0xc
	v_mov_b32_dpp v70, v240 quad_perm:[0,1,2,3] row_mask:0xf bank_mask:0x3
	v_mov_b32_dpp v71, v241 quad_perm:[0,1,2,3] row_mask:0xf bank_mask:0x3
	v_mov_b32_dpp v72, v242 quad_perm:[0,1,2,3] row_mask:0xf bank_mask:0x3
	v_mov_b32_dpp v73, v243 quad_perm:[0,1,2,3] row_mask:0xf bank_mask:0x3
	global_store_dwordx4 v250, v[86:89], s[86:87]
	global_store_dwordx4 v251, v[70:73], s[86:87]
	v_cvt_pk_bf16_f32 v62, v62, v63
	v_cvt_pk_bf16_f32 v63, v64, v65
	v_cvt_pk_bf16_f32 v64, v58, v59
	v_cvt_pk_bf16_f32 v65, v60, v61
	v_cvt_pk_bf16_f32 v46, v46, v47
	v_cvt_pk_bf16_f32 v47, v48, v49
	v_cvt_pk_bf16_f32 v48, v42, v43
	v_cvt_pk_bf16_f32 v49, v44, v45
	v_mov_b32_dpp v240, v62 row_ror:8 row_mask:0xf bank_mask:0xf
	v_mov_b32_dpp v241, v63 row_ror:8 row_mask:0xf bank_mask:0xf
	v_mov_b32_dpp v242, v64 row_ror:8 row_mask:0xf bank_mask:0xf
	v_mov_b32_dpp v243, v65 row_ror:8 row_mask:0xf bank_mask:0xf
	v_mov_b32_dpp v62, v46 row_ror:8 row_mask:0xf bank_mask:0xc
	v_mov_b32_dpp v63, v47 row_ror:8 row_mask:0xf bank_mask:0xc
	v_mov_b32_dpp v64, v48 row_ror:8 row_mask:0xf bank_mask:0xc
	v_mov_b32_dpp v65, v49 row_ror:8 row_mask:0xf bank_mask:0xc
	v_mov_b32_dpp v46, v240 quad_perm:[0,1,2,3] row_mask:0xf bank_mask:0x3
	v_mov_b32_dpp v47, v241 quad_perm:[0,1,2,3] row_mask:0xf bank_mask:0x3
	v_mov_b32_dpp v48, v242 quad_perm:[0,1,2,3] row_mask:0xf bank_mask:0x3
; DI unsigned pk_bf16(float a, float b) { f32x2 v = {a, b}; bf2_t r = __builtin_convertvector(v, bf2_t); return __builtin_bit_cast(unsigned, r); }
;     DI void operator()(const f32x4 (&acc)[2][2][4][2], const Unit& u, int wr, int wc, int fr, int fq) const {
;     ...
;             for (int m = 0; m < 4; ++m) { bf16_t* rowp = O + (size_t)(row0 + ai * HALF + m * 16) * ldc + col0;
; #pragma unroll
;                 for (int bj = 0; bj < 2; ++bj) { const f32x4 v0 = acc[ai][bj][m][0], v1 = acc[ai][bj][m][1];
;                     u32x4 w; w.x = pk_bf16(v0[0], v0[1]); w.y = pk_bf16(v0[2], v0[3]); w.z = pk_bf16(v1[0], v1[1]); w.w = pk_bf16(v1[2], v1[3]);
;                     *(u32x4*)(rowp + bj * HALF) = w; } }
; template <class Epi, class Sched>
; DI void gemm_phase(LAS unsigned char* lds, const Gemm g, const Sched& S, const Epi& E) {
;     ...
;         E(acc, cur, wr, wc, fr, fq);
;         if (!has_next) break;
	v_mov_b32_dpp v49, v243 quad_perm:[0,1,2,3] row_mask:0xf bank_mask:0x3
	global_store_dwordx4 v252, v[62:65], s[86:87]
	global_store_dwordx4 v253, v[46:49], s[86:87]
	v_cvt_pk_bf16_f32 v54, v54, v55
	v_cvt_pk_bf16_f32 v55, v56, v57
	v_cvt_pk_bf16_f32 v56, v50, v51
	v_cvt_pk_bf16_f32 v57, v52, v53
	v_cvt_pk_bf16_f32 v30, v30, v31
	v_cvt_pk_bf16_f32 v31, v32, v33
	v_cvt_pk_bf16_f32 v32, v26, v27
	v_cvt_pk_bf16_f32 v33, v28, v29
	v_mov_b32_dpp v240, v54 row_ror:8 row_mask:0xf bank_mask:0xf
	v_mov_b32_dpp v241, v55 row_ror:8 row_mask:0xf bank_mask:0xf
	v_mov_b32_dpp v242, v56 row_ror:8 row_mask:0xf bank_mask:0xf
	v_mov_b32_dpp v243, v57 row_ror:8 row_mask:0xf bank_mask:0xf
	v_mov_b32_dpp v54, v30 row_ror:8 row_mask:0xf bank_mask:0xc
	v_mov_b32_dpp v55, v31 row_ror:8 row_mask:0xf bank_mask:0xc
	v_mov_b32_dpp v56, v32 row_ror:8 row_mask:0xf bank_mask:0xc
	v_mov_b32_dpp v57, v33 row_ror:8 row_mask:0xf bank_mask:0xc
	v_mov_b32_dpp v30, v240 quad_perm:[0,1,2,3] row_mask:0xf bank_mask:0x3
	v_mov_b32_dpp v31, v241 quad_perm:[0,1,2,3] row_mask:0xf bank_mask:0x3
	v_mov_b32_dpp v32, v242 quad_perm:[0,1,2,3] row_mask:0xf bank_mask:0x3
	v_mov_b32_dpp v33, v243 quad_perm:[0,1,2,3] row_mask:0xf bank_mask:0x3
	global_store_dwordx4 v254, v[54:57], s[86:87]
	global_store_dwordx4 v255, v[30:33], s[86:87]
	v_cvt_pk_bf16_f32 v38, v38, v39
	v_cvt_pk_bf16_f32 v39, v40, v41
	v_cvt_pk_bf16_f32 v40, v34, v35
	v_cvt_pk_bf16_f32 v41, v36, v37
	v_cvt_pk_bf16_f32 v14, v14, v15
	v_cvt_pk_bf16_f32 v15, v16, v17
	v_cvt_pk_bf16_f32 v16, v10, v11
	v_cvt_pk_bf16_f32 v17, v12, v13
	v_mov_b32_dpp v240, v38 row_ror:8 row_mask:0xf bank_mask:0xf
	v_mov_b32_dpp v241, v39 row_ror:8 row_mask:0xf bank_mask:0xf
	v_mov_b32_dpp v242, v40 row_ror:8 row_mask:0xf bank_mask:0xf
	v_mov_b32_dpp v243, v41 row_ror:8 row_mask:0xf bank_mask:0xf
	v_mov_b32_dpp v38, v14 row_ror:8 row_mask:0xf bank_mask:0xc
	v_mov_b32_dpp v39, v15 row_ror:8 row_mask:0xf bank_mask:0xc
	v_mov_b32_dpp v40, v16 row_ror:8 row_mask:0xf bank_mask:0xc
	v_mov_b32_dpp v41, v17 row_ror:8 row_mask:0xf bank_mask:0xc
	v_mov_b32_dpp v14, v240 quad_perm:[0,1,2,3] row_mask:0xf bank_mask:0x3
	v_mov_b32_dpp v15, v241 quad_perm:[0,1,2,3] row_mask:0xf bank_mask:0x3
	v_mov_b32_dpp v16, v242 quad_perm:[0,1,2,3] row_mask:0xf bank_mask:0x3
	v_mov_b32_dpp v17, v243 quad_perm:[0,1,2,3] row_mask:0xf bank_mask:0x3
	global_store_dwordx4 v154, v[38:41], s[86:87]
	global_store_dwordx4 v155, v[14:17], s[86:87]
	v_cvt_pk_bf16_f32 v22, v22, v23
	v_cvt_pk_bf16_f32 v23, v24, v25
	v_cvt_pk_bf16_f32 v24, v18, v19
	v_cvt_pk_bf16_f32 v25, v20, v21
	v_cvt_pk_bf16_f32 v6, v6, v7
	v_cvt_pk_bf16_f32 v7, v8, v9
	v_cvt_pk_bf16_f32 v8, v2, v3
	v_cvt_pk_bf16_f32 v9, v4, v5
	v_mov_b32_dpp v240, v22 row_ror:8 row_mask:0xf bank_mask:0xf
	v_mov_b32_dpp v241, v23 row_ror:8 row_mask:0xf bank_mask:0xf
	v_mov_b32_dpp v242, v24 row_ror:8 row_mask:0xf bank_mask:0xf
	v_mov_b32_dpp v243, v25 row_ror:8 row_mask:0xf bank_mask:0xf
	v_mov_b32_dpp v22, v6 row_ror:8 row_mask:0xf bank_mask:0xc
	v_mov_b32_dpp v23, v7 row_ror:8 row_mask:0xf bank_mask:0xc
	v_mov_b32_dpp v24, v8 row_ror:8 row_mask:0xf bank_mask:0xc
	v_mov_b32_dpp v25, v9 row_ror:8 row_mask:0xf bank_mask:0xc
	v_mov_b32_dpp v6, v240 quad_perm:[0,1,2,3] row_mask:0xf bank_mask:0x3
	v_mov_b32_dpp v7, v241 quad_perm:[0,1,2,3] row_mask:0xf bank_mask:0x3
	v_mov_b32_dpp v8, v242 quad_perm:[0,1,2,3] row_mask:0xf bank_mask:0x3
	v_mov_b32_dpp v9, v243 quad_perm:[0,1,2,3] row_mask:0xf bank_mask:0x3
	global_store_dwordx4 v156, v[22:25], s[86:87]
	global_store_dwordx4 v157, v[6:9], s[86:87]
	s_cbranch_vccz .LBB0_1187
	s_waitcnt vmcnt(0)
	s_cmpk_gt_u32 s3, 0xff
	s_cbranch_scc1 .LBB0_1194
	s_barrier
